# diff attention loop: operand-stationary MFMA order for QK^T and P.V (48 adjacent independent MFMAs swapped, first QK chain of each key tile given its own temp): consecutive MFMAs change only one input
# baseline (speedup 1.0000x reference)
.LBB0_444:
	ds_read_b64_tr_b16 v[158:159], v203
	ds_read_b64_tr_b16 v[160:161], v203 offset:2048
	s_waitcnt lgkmcnt(9)
	v_mfma_f32_16x16x32_bf16 v[140:143], v[110:113], v[10:13], 0
	s_waitcnt lgkmcnt(7)
	v_mfma_f32_16x16x32_bf16 v[110:113], v[110:113], v[18:21], 0
	ds_read_b64_tr_b16 v[162:163], v204
	ds_read_b64_tr_b16 v[164:165], v204 offset:2048
	v_mfma_f32_16x16x32_bf16 v[152:155], v[26:29], v[14:17], v[140:143]
	v_mfma_f32_16x16x32_bf16 v[144:147], v[26:29], v[22:25], v[110:113]
	ds_read_b64_tr_b16 v[166:167], v205
	ds_read_b64_tr_b16 v[168:169], v205 offset:2048
	v_mfma_f32_16x16x32_bf16 v[248:251], v[116:119], v[10:13], 0
	s_waitcnt lgkmcnt(10)
	v_mfma_f32_16x16x32_bf16 v[26:29], v[116:119], v[18:21], 0
	ds_read_b64_tr_b16 v[170:171], v206
	ds_read_b64_tr_b16 v[172:173], v206 offset:2048
	v_mfma_f32_16x16x32_bf16 v[148:151], v[120:123], v[14:17], v[248:251]
	v_mfma_f32_16x16x32_bf16 v[140:143], v[120:123], v[22:25], v[26:29]
	ds_read_b64_tr_b16 v[174:175], v203 offset:8192
	ds_read_b64_tr_b16 v[176:177], v203 offset:10240
	s_waitcnt lgkmcnt(13)
	v_mfma_f32_16x16x32_bf16 v[248:251], v[124:127], v[10:13], 0
	s_waitcnt lgkmcnt(11)
	v_mfma_f32_16x16x32_bf16 v[26:29], v[124:127], v[18:21], 0
	ds_read_b64_tr_b16 v[208:209], v204 offset:8192
	ds_read_b64_tr_b16 v[210:211], v204 offset:10240
	v_mfma_f32_16x16x32_bf16 v[110:113], v[132:135], v[14:17], v[248:251]
	v_mfma_f32_16x16x32_bf16 v[116:119], v[132:135], v[22:25], v[26:29]
	ds_read_b64_tr_b16 v[132:133], v205 offset:8192
	ds_read_b64_tr_b16 v[134:135], v205 offset:10240
	v_mfma_f32_16x16x32_bf16 v[248:251], v[128:131], v[10:13], 0
	s_waitcnt lgkmcnt(14)
	v_mfma_f32_16x16x32_bf16 v[26:29], v[128:131], v[18:21], 0
	ds_read_b64_tr_b16 v[212:213], v206 offset:8192
	ds_read_b64_tr_b16 v[214:215], v206 offset:10240
	v_mfma_f32_16x16x32_bf16 v[120:123], v[136:139], v[14:17], v[248:251]
	v_mfma_f32_16x16x32_bf16 v[124:127], v[136:139], v[22:25], v[26:29]
	s_add_u32 s68, s14, 0xfcfe0000
	s_addc_u32 s69, s15, -1
	s_mov_b32 s74, m0
	s_mov_b32 m0, s30
	s_nop 0
	global_load_lds_dwordx4 v157, s[68:69]
	s_mov_b32 m0, s74
	s_add_u32 s68, s14, 0xfcfe0080
	s_addc_u32 s69, s15, -1
	s_mov_b32 s74, m0
	s_mov_b32 m0, s31
	s_nop 0
	global_load_lds_dwordx4 v157, s[68:69]
	s_mov_b32 m0, s74
	s_add_u32 s74, s14, 0xfffd0000
	s_addc_u32 s75, s15, -1
	s_add_i32 s68, s38, 0xc000
	s_mov_b32 s69, m0
	s_mov_b32 m0, s68
	s_nop 0
	global_load_lds_dwordx4 v156, s[74:75]
	s_mov_b32 m0, s69
	s_add_u32 s74, s14, 0xfffd0080
	s_addc_u32 s75, s15, -1
	s_add_i32 s69, s39, 0xc000
	s_mov_b32 s76, m0
	s_mov_b32 m0, s69
	s_nop 0
	global_load_lds_dwordx4 v156, s[74:75]
	s_mov_b32 m0, s76
	ds_read_b64_tr_b16 v[128:129], v203 offset:4096
	ds_read_b64_tr_b16 v[130:131], v203 offset:6144
	v_mov_b64_e32 v[28:29], s[6:7]
	v_mov_b64_e32 v[26:27], s[4:5]
	s_waitcnt lgkmcnt(14)
	v_mfma_f32_16x16x32_bf16 v[98:101], v[6:9], v[158:161], v[98:101]
	v_exp_f32_e32 v152, v152
	v_mfma_f32_16x16x32_bf16 v[106:109], v[6:9], v[26:29], v[106:109]
	v_mfma_f32_16x16x32_bf16 v[102:105], v[2:5], v[26:29], v[102:105]
	v_exp_f32_e32 v153, v153
	v_mfma_f32_16x16x32_bf16 v[90:93], v[2:5], v[158:161], v[90:93]
	ds_read_b64_tr_b16 v[136:137], v204 offset:4096
	ds_read_b64_tr_b16 v[138:139], v204 offset:6144
	v_mfma_f32_16x16x32_bf16 v[82:85], v[2:5], v[162:165], v[82:85]
	v_exp_f32_e32 v154, v154
	v_mfma_f32_16x16x32_bf16 v[94:97], v[6:9], v[162:165], v[94:97]
	v_exp_f32_e32 v155, v155
	ds_read_b64_tr_b16 v[158:159], v205 offset:4096
	ds_read_b64_tr_b16 v[160:161], v205 offset:6144
	s_waitcnt lgkmcnt(14)
	v_mfma_f32_16x16x32_bf16 v[86:89], v[6:9], v[166:169], v[86:89]
	v_exp_f32_e32 v144, v144
	s_nop 0
	v_exp_f32_e32 v145, v145
	v_mfma_f32_16x16x32_bf16 v[162:165], v[2:5], v[166:169], v[74:77]
	ds_read_b64_tr_b16 v[166:167], v206 offset:4096
	ds_read_b64_tr_b16 v[168:169], v206 offset:6144
	v_exp_f32_e32 v146, v146
	v_mfma_f32_16x16x32_bf16 v[216:219], v[6:9], v[170:173], v[78:81]
	s_nop 0
	v_exp_f32_e32 v147, v147
	v_mfma_f32_16x16x32_bf16 v[170:173], v[2:5], v[170:173], v[66:69]
	ds_read_b64_tr_b16 v[220:221], v203 offset:12288
	ds_read_b64_tr_b16 v[222:223], v203 offset:14336
	v_exp_f32_e32 v148, v148
	s_waitcnt lgkmcnt(14)
	v_mfma_f32_16x16x32_bf16 v[58:61], v[2:5], v[174:177], v[58:61]
	v_mfma_f32_16x16x32_bf16 v[224:227], v[6:9], v[174:177], v[70:73]
	v_exp_f32_e32 v149, v149
	ds_read_b64_tr_b16 v[174:175], v204 offset:12288
	ds_read_b64_tr_b16 v[176:177], v204 offset:14336
	v_exp_f32_e32 v150, v150
	v_mfma_f32_16x16x32_bf16 v[228:231], v[6:9], v[208:211], v[62:65]
	v_mfma_f32_16x16x32_bf16 v[50:53], v[2:5], v[208:211], v[50:53]
	v_exp_f32_e32 v151, v151
	ds_read_b64_tr_b16 v[208:209], v205 offset:12288
	ds_read_b64_tr_b16 v[210:211], v205 offset:14336
	s_waitcnt lgkmcnt(14)
	v_mfma_f32_16x16x32_bf16 v[42:45], v[2:5], v[132:135], v[42:45]
	v_exp_f32_e32 v140, v140
	v_mfma_f32_16x16x32_bf16 v[54:57], v[6:9], v[132:135], v[54:57]
	v_exp_f32_e32 v141, v141
	ds_read_b64_tr_b16 v[232:233], v206 offset:12288
	ds_read_b64_tr_b16 v[234:235], v206 offset:14336
	v_mfma_f32_16x16x32_bf16 v[46:49], v[6:9], v[212:215], v[46:49]
	v_exp_f32_e32 v142, v142
	s_nop 0
	v_exp_f32_e32 v143, v143
	v_mfma_f32_16x16x32_bf16 v[212:215], v[2:5], v[212:215], v[38:41]
	s_nop 2
	ds_read_b128 v[38:41], v1 offset:32768
	v_mfma_f32_16x16x32_bf16 v[66:69], v[34:37], v[26:29], v[106:109]
	v_exp_f32_e32 v110, v110
	v_cvt_pk_bf16_f32 v6, v152, v153
	s_waitcnt lgkmcnt(14)
	v_mfma_f32_16x16x32_bf16 v[62:65], v[34:37], v[128:131], v[98:101]
	v_mfma_f32_16x16x32_bf16 v[78:81], v[30:33], v[128:131], v[90:93]
	v_exp_f32_e32 v111, v111
	v_cvt_pk_bf16_f32 v7, v154, v155
	v_mfma_f32_16x16x32_bf16 v[70:73], v[30:33], v[26:29], v[102:105]
	ds_read_b128 v[236:239], v115 offset:32768
	s_waitcnt lgkmcnt(14)
	v_mfma_f32_16x16x32_bf16 v[82:85], v[30:33], v[136:139], v[82:85]
	v_exp_f32_e32 v112, v112
	v_cvt_pk_bf16_f32 v8, v148, v149
	v_mfma_f32_16x16x32_bf16 v[74:77], v[34:37], v[136:139], v[94:97]
	v_exp_f32_e32 v113, v113
	v_cvt_pk_bf16_f32 v9, v150, v151
	ds_read_b128 v[240:243], v1 offset:34816
	s_waitcnt lgkmcnt(13)
	v_mfma_f32_16x16x32_bf16 v[90:93], v[34:37], v[158:161], v[86:89]
	v_exp_f32_e32 v116, v116
	v_cvt_pk_bf16_f32 v2, v144, v145
	v_mfma_f32_16x16x32_bf16 v[94:97], v[30:33], v[158:161], v[162:165]
	v_exp_f32_e32 v117, v117
	v_cvt_pk_bf16_f32 v3, v146, v147
	ds_read_b128 v[158:161], v115 offset:34816
	s_waitcnt lgkmcnt(12)
	v_mfma_f32_16x16x32_bf16 v[102:105], v[30:33], v[166:169], v[170:173]
	v_exp_f32_e32 v118, v118
	v_cvt_pk_bf16_f32 v4, v140, v141
	v_mfma_f32_16x16x32_bf16 v[98:101], v[34:37], v[166:169], v[216:219]
	v_exp_f32_e32 v119, v119
	v_cvt_pk_bf16_f32 v5, v142, v143
	ds_read_b128 v[162:165], v1 offset:36864
	v_exp_f32_e32 v120, v120
	s_waitcnt lgkmcnt(11)
	v_mfma_f32_16x16x32_bf16 v[148:151], v[34:37], v[220:223], v[224:227]
	s_nop 0
	v_exp_f32_e32 v121, v121
	v_mfma_f32_16x16x32_bf16 v[152:155], v[30:33], v[220:223], v[58:61]
	ds_read_b128 v[166:169], v115 offset:36864
	v_exp_f32_e32 v122, v122
	s_waitcnt lgkmcnt(10)
	v_mfma_f32_16x16x32_bf16 v[144:147], v[30:33], v[174:177], v[50:53]
	s_nop 0
	v_exp_f32_e32 v123, v123
	v_mfma_f32_16x16x32_bf16 v[140:143], v[34:37], v[174:177], v[228:231]
	s_nop 2
	ds_read_b128 v[50:53], v1 offset:38912
	s_waitcnt lgkmcnt(9)
	v_mfma_f32_16x16x32_bf16 v[132:135], v[34:37], v[208:211], v[54:57]
	v_exp_f32_e32 v124, v124
	v_mfma_f32_16x16x32_bf16 v[136:139], v[30:33], v[208:211], v[42:45]
	v_exp_f32_e32 v125, v125
	ds_read_b128 v[170:173], v115 offset:38912
	s_waitcnt lgkmcnt(8)
	v_mfma_f32_16x16x32_bf16 v[128:131], v[30:33], v[232:235], v[212:215]
	v_exp_f32_e32 v126, v126
	v_mfma_f32_16x16x32_bf16 v[106:109], v[34:37], v[232:235], v[46:49]
	v_exp_f32_e32 v127, v127
	v_cvt_pk_bf16_f32 v34, v110, v111
	v_cvt_pk_bf16_f32 v35, v112, v113
	v_cvt_pk_bf16_f32 v36, v120, v121
	v_cvt_pk_bf16_f32 v37, v122, v123
	v_cvt_pk_bf16_f32 v30, v116, v117
	v_cvt_pk_bf16_f32 v31, v118, v119
	v_cvt_pk_bf16_f32 v32, v124, v125
	v_cvt_pk_bf16_f32 v33, v126, v127
	s_waitcnt vmcnt(4)
	s_barrier
	ds_read_b64_tr_b16 v[116:117], v203 offset:16384
	ds_read_b64_tr_b16 v[118:119], v203 offset:18432
	s_waitcnt lgkmcnt(9)
	v_mfma_f32_16x16x32_bf16 v[42:45], v[38:41], v[10:13], 0
	s_waitcnt lgkmcnt(8)
	v_mfma_f32_16x16x32_bf16 v[248:251], v[38:41], v[18:21], 0
	ds_read_b64_tr_b16 v[120:121], v204 offset:16384
	ds_read_b64_tr_b16 v[122:123], v204 offset:18432
	v_mfma_f32_16x16x32_bf16 v[110:113], v[236:239], v[14:17], v[42:45]
	v_mfma_f32_16x16x32_bf16 v[58:61], v[236:239], v[22:25], v[248:251]
	ds_read_b64_tr_b16 v[124:125], v205 offset:16384
	ds_read_b64_tr_b16 v[126:127], v205 offset:18432
	s_waitcnt lgkmcnt(11)
	v_mfma_f32_16x16x32_bf16 v[38:41], v[240:243], v[10:13], 0
	s_waitcnt lgkmcnt(10)
	v_mfma_f32_16x16x32_bf16 v[248:251], v[240:243], v[18:21], 0
	ds_read_b64_tr_b16 v[174:175], v206 offset:16384
	ds_read_b64_tr_b16 v[176:177], v206 offset:18432
	v_mfma_f32_16x16x32_bf16 v[86:89], v[158:161], v[14:17], v[38:41]
	v_mfma_f32_16x16x32_bf16 v[54:57], v[158:161], v[22:25], v[248:251]
	ds_read_b64_tr_b16 v[158:159], v203 offset:24576
	ds_read_b64_tr_b16 v[160:161], v203 offset:26624
	s_waitcnt lgkmcnt(13)
	v_mfma_f32_16x16x32_bf16 v[38:41], v[162:165], v[10:13], 0
	s_waitcnt lgkmcnt(12)
	v_mfma_f32_16x16x32_bf16 v[42:45], v[162:165], v[18:21], 0
	ds_read_b64_tr_b16 v[208:209], v204 offset:24576
	ds_read_b64_tr_b16 v[210:211], v204 offset:26624
	v_mfma_f32_16x16x32_bf16 v[38:41], v[166:169], v[14:17], v[38:41]
	v_mfma_f32_16x16x32_bf16 v[42:45], v[166:169], v[22:25], v[42:45]
	ds_read_b64_tr_b16 v[162:163], v205 offset:24576
	ds_read_b64_tr_b16 v[164:165], v205 offset:26624
	s_waitcnt lgkmcnt(14)
	v_mfma_f32_16x16x32_bf16 v[46:49], v[50:53], v[10:13], 0
	v_mfma_f32_16x16x32_bf16 v[50:53], v[50:53], v[18:21], 0
	ds_read_b64_tr_b16 v[166:167], v206 offset:24576
	ds_read_b64_tr_b16 v[168:169], v206 offset:26624
	v_mfma_f32_16x16x32_bf16 v[46:49], v[170:173], v[14:17], v[46:49]
	v_mfma_f32_16x16x32_bf16 v[50:53], v[170:173], v[22:25], v[50:53]
	s_add_u32 s74, s14, 0xfcff0000
	s_addc_u32 s75, s15, -1
	s_mov_b32 s76, m0
	s_mov_b32 m0, s40
	s_nop 0
	global_load_lds_dwordx4 v157, s[74:75]
	s_mov_b32 m0, s76
	s_add_u32 s74, s14, 0xfcff0080
	s_addc_u32 s75, s15, -1
	s_mov_b32 s76, m0
	s_mov_b32 m0, s41
	s_nop 0
	global_load_lds_dwordx4 v157, s[74:75]
	s_mov_b32 m0, s76
	s_add_u32 s74, s14, 0xfffe0000
	s_addc_u32 s75, s15, -1
	s_mov_b32 s76, m0
	s_mov_b32 m0, s38
	s_nop 0
	global_load_lds_dwordx4 v156, s[74:75]
	s_mov_b32 m0, s76
	s_add_u32 s74, s14, 0xfffe0080
	s_addc_u32 s75, s15, -1
	s_mov_b32 s76, m0
	s_mov_b32 m0, s39
	s_nop 0
	global_load_lds_dwordx4 v156, s[74:75]
	s_mov_b32 m0, s76
	ds_read_b64_tr_b16 v[170:171], v203 offset:20480
	ds_read_b64_tr_b16 v[172:173], v203 offset:22528
	v_mfma_f32_16x16x32_bf16 v[66:69], v[6:9], v[26:29], v[66:69]
	v_exp_f32_e32 v110, v110
	s_waitcnt lgkmcnt(14)
	v_mfma_f32_16x16x32_bf16 v[62:65], v[6:9], v[116:119], v[62:65]
	v_mfma_f32_16x16x32_bf16 v[78:81], v[2:5], v[116:119], v[78:81]
	v_exp_f32_e32 v111, v111
	v_mfma_f32_16x16x32_bf16 v[70:73], v[2:5], v[26:29], v[70:73]
	ds_read_b64_tr_b16 v[116:117], v204 offset:20480
	ds_read_b64_tr_b16 v[118:119], v204 offset:22528
	v_mfma_f32_16x16x32_bf16 v[82:85], v[2:5], v[120:123], v[82:85]
	v_exp_f32_e32 v112, v112
	v_mfma_f32_16x16x32_bf16 v[74:77], v[6:9], v[120:123], v[74:77]
	v_exp_f32_e32 v113, v113
	ds_read_b64_tr_b16 v[120:121], v205 offset:20480
	ds_read_b64_tr_b16 v[122:123], v205 offset:22528
	s_waitcnt lgkmcnt(14)
	v_mfma_f32_16x16x32_bf16 v[90:93], v[6:9], v[124:127], v[90:93]
	v_exp_f32_e32 v58, v58
	v_mfma_f32_16x16x32_bf16 v[94:97], v[2:5], v[124:127], v[94:97]
	v_exp_f32_e32 v59, v59
	ds_read_b64_tr_b16 v[124:125], v206 offset:20480
	ds_read_b64_tr_b16 v[126:127], v206 offset:22528
	v_mfma_f32_16x16x32_bf16 v[102:105], v[2:5], v[174:177], v[102:105]
	v_exp_f32_e32 v60, v60
	v_mfma_f32_16x16x32_bf16 v[98:101], v[6:9], v[174:177], v[98:101]
	v_exp_f32_e32 v61, v61
	ds_read_b64_tr_b16 v[174:175], v203 offset:28672
	ds_read_b64_tr_b16 v[176:177], v203 offset:30720
	v_exp_f32_e32 v86, v86
	s_waitcnt lgkmcnt(14)
	v_mfma_f32_16x16x32_bf16 v[148:151], v[6:9], v[158:161], v[148:151]
	s_nop 0
	v_exp_f32_e32 v87, v87
	v_mfma_f32_16x16x32_bf16 v[152:155], v[2:5], v[158:161], v[152:155]
	ds_read_b64_tr_b16 v[158:159], v204 offset:28672
	ds_read_b64_tr_b16 v[160:161], v204 offset:30720
	v_exp_f32_e32 v88, v88
	v_mfma_f32_16x16x32_bf16 v[212:215], v[6:9], v[208:211], v[140:143]
	s_nop 0
	v_exp_f32_e32 v89, v89
	v_mfma_f32_16x16x32_bf16 v[208:211], v[2:5], v[208:211], v[144:147]
	ds_read_b64_tr_b16 v[216:217], v205 offset:28672
	ds_read_b64_tr_b16 v[218:219], v205 offset:30720
	v_exp_f32_e32 v54, v54
	s_waitcnt lgkmcnt(14)
	v_mfma_f32_16x16x32_bf16 v[220:223], v[6:9], v[162:165], v[132:135]
	s_nop 0
	v_exp_f32_e32 v55, v55
	v_mfma_f32_16x16x32_bf16 v[162:165], v[2:5], v[162:165], v[136:139]
	ds_read_b64_tr_b16 v[224:225], v206 offset:28672
	ds_read_b64_tr_b16 v[226:227], v206 offset:30720
	v_mfma_f32_16x16x32_bf16 v[106:109], v[6:9], v[166:169], v[106:109]
	v_exp_f32_e32 v56, v56
	s_nop 0
	v_exp_f32_e32 v57, v57
	v_mfma_f32_16x16x32_bf16 v[166:169], v[2:5], v[166:169], v[128:131]
	ds_read_b128 v[144:147], v1 offset:49152
	v_mfma_f32_16x16x32_bf16 v[66:69], v[34:37], v[26:29], v[66:69]
	v_exp_f32_e32 v38, v38
	v_cvt_pk_bf16_f32 v6, v110, v111
	s_waitcnt lgkmcnt(14)
	v_mfma_f32_16x16x32_bf16 v[62:65], v[34:37], v[170:173], v[62:65]
	v_mfma_f32_16x16x32_bf16 v[78:81], v[30:33], v[170:173], v[78:81]
	v_exp_f32_e32 v39, v39
	v_cvt_pk_bf16_f32 v7, v112, v113
	v_mfma_f32_16x16x32_bf16 v[70:73], v[30:33], v[26:29], v[70:73]
	ds_read_b128 v[170:173], v115 offset:49152
	s_waitcnt lgkmcnt(14)
	v_mfma_f32_16x16x32_bf16 v[82:85], v[30:33], v[116:119], v[82:85]
	v_exp_f32_e32 v40, v40
	v_cvt_pk_bf16_f32 v8, v86, v87
	v_mfma_f32_16x16x32_bf16 v[74:77], v[34:37], v[116:119], v[74:77]
	v_exp_f32_e32 v41, v41
	v_cvt_pk_bf16_f32 v9, v88, v89
	ds_read_b128 v[228:231], v1 offset:51200
	s_waitcnt lgkmcnt(13)
	v_mfma_f32_16x16x32_bf16 v[90:93], v[34:37], v[120:123], v[90:93]
	v_exp_f32_e32 v42, v42
	v_cvt_pk_bf16_f32 v2, v58, v59
	v_mfma_f32_16x16x32_bf16 v[94:97], v[30:33], v[120:123], v[94:97]
	v_exp_f32_e32 v43, v43
	v_cvt_pk_bf16_f32 v3, v60, v61
	ds_read_b128 v[232:235], v115 offset:51200
	s_waitcnt lgkmcnt(12)
	v_mfma_f32_16x16x32_bf16 v[102:105], v[30:33], v[124:127], v[102:105]
	v_exp_f32_e32 v44, v44
	v_cvt_pk_bf16_f32 v4, v54, v55
	v_mfma_f32_16x16x32_bf16 v[98:101], v[34:37], v[124:127], v[98:101]
	v_exp_f32_e32 v45, v45
	v_cvt_pk_bf16_f32 v5, v56, v57
	ds_read_b128 v[236:239], v1 offset:53248
	s_waitcnt lgkmcnt(11)
	v_mfma_f32_16x16x32_bf16 v[136:139], v[34:37], v[174:177], v[148:151]
	v_exp_f32_e32 v46, v46
	s_nop 0
	v_exp_f32_e32 v47, v47
	v_mfma_f32_16x16x32_bf16 v[140:143], v[30:33], v[174:177], v[152:155]
	ds_read_b128 v[148:151], v115 offset:53248
	s_waitcnt lgkmcnt(10)
	v_mfma_f32_16x16x32_bf16 v[132:135], v[30:33], v[158:161], v[208:211]
	v_exp_f32_e32 v48, v48
	v_mfma_f32_16x16x32_bf16 v[128:131], v[34:37], v[158:161], v[212:215]
	v_exp_f32_e32 v49, v49
	ds_read_b128 v[152:155], v1 offset:55296
	s_waitcnt lgkmcnt(9)
	v_mfma_f32_16x16x32_bf16 v[120:123], v[34:37], v[216:219], v[220:223]
	v_exp_f32_e32 v50, v50
	v_mfma_f32_16x16x32_bf16 v[124:127], v[30:33], v[216:219], v[162:165]
	v_exp_f32_e32 v51, v51
	ds_read_b128 v[158:161], v115 offset:55296
	s_waitcnt lgkmcnt(8)
	v_mfma_f32_16x16x32_bf16 v[110:113], v[30:33], v[224:227], v[166:169]
	v_exp_f32_e32 v52, v52
	v_mfma_f32_16x16x32_bf16 v[106:109], v[34:37], v[224:227], v[106:109]
	v_exp_f32_e32 v53, v53
	v_cvt_pk_bf16_f32 v34, v38, v39
	v_cvt_pk_bf16_f32 v35, v40, v41
	v_cvt_pk_bf16_f32 v36, v46, v47
	v_cvt_pk_bf16_f32 v37, v48, v49
	v_cvt_pk_bf16_f32 v30, v42, v43
	v_cvt_pk_bf16_f32 v31, v44, v45
	v_cvt_pk_bf16_f32 v32, v50, v51
	v_cvt_pk_bf16_f32 v33, v52, v53
	s_waitcnt vmcnt(4)
	s_barrier
	ds_read_b64_tr_b16 v[162:163], v203 offset:32768
	ds_read_b64_tr_b16 v[164:165], v203 offset:34816
	s_waitcnt lgkmcnt(9)
	v_mfma_f32_16x16x32_bf16 v[248:251], v[144:147], v[10:13], 0
	s_waitcnt lgkmcnt(8)
	v_mfma_f32_16x16x32_bf16 v[38:41], v[144:147], v[18:21], 0
	ds_read_b64_tr_b16 v[166:167], v204 offset:32768
	ds_read_b64_tr_b16 v[168:169], v204 offset:34816
	v_mfma_f32_16x16x32_bf16 v[116:119], v[170:173], v[14:17], v[248:251]
	v_mfma_f32_16x16x32_bf16 v[58:61], v[170:173], v[22:25], v[38:41]
	ds_read_b64_tr_b16 v[144:145], v205 offset:32768
	ds_read_b64_tr_b16 v[146:147], v205 offset:34816
	s_waitcnt lgkmcnt(11)
	v_mfma_f32_16x16x32_bf16 v[248:251], v[228:231], v[10:13], 0
	s_waitcnt lgkmcnt(10)
	v_mfma_f32_16x16x32_bf16 v[38:41], v[228:231], v[18:21], 0
	ds_read_b64_tr_b16 v[170:171], v206 offset:32768
	ds_read_b64_tr_b16 v[172:173], v206 offset:34816
	v_mfma_f32_16x16x32_bf16 v[86:89], v[232:235], v[14:17], v[248:251]
	v_mfma_f32_16x16x32_bf16 v[54:57], v[232:235], v[22:25], v[38:41]
	ds_read_b64_tr_b16 v[174:175], v203 offset:40960
	ds_read_b64_tr_b16 v[176:177], v203 offset:43008
	s_waitcnt lgkmcnt(13)
	v_mfma_f32_16x16x32_bf16 v[38:41], v[236:239], v[10:13], 0
	s_waitcnt lgkmcnt(12)
	v_mfma_f32_16x16x32_bf16 v[42:45], v[236:239], v[18:21], 0
	ds_read_b64_tr_b16 v[208:209], v204 offset:40960
	ds_read_b64_tr_b16 v[210:211], v204 offset:43008
	v_mfma_f32_16x16x32_bf16 v[38:41], v[148:151], v[14:17], v[38:41]
	v_mfma_f32_16x16x32_bf16 v[42:45], v[148:151], v[22:25], v[42:45]
	ds_read_b64_tr_b16 v[148:149], v205 offset:40960
	ds_read_b64_tr_b16 v[150:151], v205 offset:43008
	s_waitcnt lgkmcnt(14)
	v_mfma_f32_16x16x32_bf16 v[46:49], v[152:155], v[10:13], 0
	v_mfma_f32_16x16x32_bf16 v[50:53], v[152:155], v[18:21], 0
	ds_read_b64_tr_b16 v[212:213], v206 offset:40960
	ds_read_b64_tr_b16 v[214:215], v206 offset:43008
	v_mfma_f32_16x16x32_bf16 v[46:49], v[158:161], v[14:17], v[46:49]
	v_mfma_f32_16x16x32_bf16 v[50:53], v[158:161], v[22:25], v[50:53]
	s_add_u32 s74, s14, 0xfd000000
	s_addc_u32 s75, s15, -1
	s_mov_b32 s76, m0
	s_mov_b32 m0, s52
	s_nop 0
	global_load_lds_dwordx4 v157, s[74:75]
	s_mov_b32 m0, s76
	s_add_u32 s74, s14, 0xfd000080
	s_addc_u32 s75, s15, -1
	s_mov_b32 s76, m0
	s_mov_b32 m0, s53
	s_nop 0
	global_load_lds_dwordx4 v157, s[74:75]
	s_mov_b32 m0, s76
	s_add_u32 s74, s14, 0xffff0000
	s_addc_u32 s75, s15, -1
	s_mov_b32 s76, m0
	s_mov_b32 m0, s62
	s_nop 0
	global_load_lds_dwordx4 v156, s[74:75]
	s_mov_b32 m0, s76
	s_add_u32 s74, s14, 0xffff0080
	s_addc_u32 s75, s15, -1
	s_mov_b32 s76, m0
	s_mov_b32 m0, s63
	s_nop 0
	global_load_lds_dwordx4 v156, s[74:75]
	s_mov_b32 m0, s76
	ds_read_b64_tr_b16 v[152:153], v203 offset:36864
	ds_read_b64_tr_b16 v[154:155], v203 offset:38912
	v_mfma_f32_16x16x32_bf16 v[66:69], v[6:9], v[26:29], v[66:69]
	v_exp_f32_e32 v116, v116
	s_waitcnt lgkmcnt(14)
	v_mfma_f32_16x16x32_bf16 v[62:65], v[6:9], v[162:165], v[62:65]
	v_mfma_f32_16x16x32_bf16 v[78:81], v[2:5], v[162:165], v[78:81]
	v_exp_f32_e32 v117, v117
	v_mfma_f32_16x16x32_bf16 v[70:73], v[2:5], v[26:29], v[70:73]
	ds_read_b64_tr_b16 v[158:159], v204 offset:36864
	ds_read_b64_tr_b16 v[160:161], v204 offset:38912
	v_mfma_f32_16x16x32_bf16 v[82:85], v[2:5], v[166:169], v[82:85]
	v_exp_f32_e32 v118, v118
	v_mfma_f32_16x16x32_bf16 v[74:77], v[6:9], v[166:169], v[74:77]
	v_exp_f32_e32 v119, v119
	ds_read_b64_tr_b16 v[162:163], v205 offset:36864
	ds_read_b64_tr_b16 v[164:165], v205 offset:38912
	s_waitcnt lgkmcnt(14)
	v_mfma_f32_16x16x32_bf16 v[90:93], v[6:9], v[144:147], v[90:93]
	v_exp_f32_e32 v58, v58
	v_mfma_f32_16x16x32_bf16 v[94:97], v[2:5], v[144:147], v[94:97]
	v_exp_f32_e32 v59, v59
	ds_read_b64_tr_b16 v[144:145], v206 offset:36864
	ds_read_b64_tr_b16 v[146:147], v206 offset:38912
	v_mfma_f32_16x16x32_bf16 v[102:105], v[2:5], v[170:173], v[102:105]
	v_exp_f32_e32 v60, v60
	v_mfma_f32_16x16x32_bf16 v[98:101], v[6:9], v[170:173], v[98:101]
	v_exp_f32_e32 v61, v61
	ds_read_b64_tr_b16 v[166:167], v203 offset:45056
	ds_read_b64_tr_b16 v[168:169], v203 offset:47104
	s_waitcnt lgkmcnt(14)
	v_mfma_f32_16x16x32_bf16 v[136:139], v[6:9], v[174:177], v[136:139]
	v_exp_f32_e32 v86, v86
	s_nop 0
	v_exp_f32_e32 v87, v87
	v_mfma_f32_16x16x32_bf16 v[140:143], v[2:5], v[174:177], v[140:143]
	ds_read_b64_tr_b16 v[170:171], v204 offset:45056
	ds_read_b64_tr_b16 v[172:173], v204 offset:47104
	v_exp_f32_e32 v88, v88
	v_mfma_f32_16x16x32_bf16 v[132:135], v[2:5], v[208:211], v[132:135]
	v_mfma_f32_16x16x32_bf16 v[174:177], v[6:9], v[208:211], v[128:131]
	v_exp_f32_e32 v89, v89
	ds_read_b64_tr_b16 v[208:209], v205 offset:45056
	ds_read_b64_tr_b16 v[210:211], v205 offset:47104
	v_exp_f32_e32 v54, v54
	s_waitcnt lgkmcnt(14)
	v_mfma_f32_16x16x32_bf16 v[216:219], v[6:9], v[148:151], v[120:123]
	s_nop 0
	v_exp_f32_e32 v55, v55
	v_mfma_f32_16x16x32_bf16 v[148:151], v[2:5], v[148:151], v[124:127]
	ds_read_b64_tr_b16 v[220:221], v206 offset:45056
	ds_read_b64_tr_b16 v[222:223], v206 offset:47104
	v_exp_f32_e32 v56, v56
	v_mfma_f32_16x16x32_bf16 v[224:227], v[6:9], v[212:215], v[106:109]
	s_nop 0
	v_exp_f32_e32 v57, v57
	v_mfma_f32_16x16x32_bf16 v[212:215], v[2:5], v[212:215], v[110:113]
	ds_read_b128 v[128:131], v1
	v_mfma_f32_16x16x32_bf16 v[66:69], v[34:37], v[26:29], v[66:69]
	v_exp_f32_e32 v38, v38
	v_cvt_pk_bf16_f32 v6, v116, v117
	s_waitcnt lgkmcnt(14)
	v_mfma_f32_16x16x32_bf16 v[62:65], v[34:37], v[152:155], v[62:65]
	v_mfma_f32_16x16x32_bf16 v[78:81], v[30:33], v[152:155], v[78:81]
	v_exp_f32_e32 v39, v39
	v_cvt_pk_bf16_f32 v7, v118, v119
	v_mfma_f32_16x16x32_bf16 v[70:73], v[30:33], v[26:29], v[70:73]
	ds_read_b128 v[152:155], v115
	s_waitcnt lgkmcnt(14)
	v_mfma_f32_16x16x32_bf16 v[82:85], v[30:33], v[158:161], v[82:85]
	v_exp_f32_e32 v40, v40
	v_cvt_pk_bf16_f32 v8, v86, v87
	v_mfma_f32_16x16x32_bf16 v[74:77], v[34:37], v[158:161], v[74:77]
	v_exp_f32_e32 v41, v41
	v_cvt_pk_bf16_f32 v9, v88, v89
	ds_read_b128 v[158:161], v1 offset:2048
	s_waitcnt lgkmcnt(13)
	v_mfma_f32_16x16x32_bf16 v[86:89], v[34:37], v[162:165], v[90:93]
	v_exp_f32_e32 v42, v42
	v_cvt_pk_bf16_f32 v2, v58, v59
	v_mfma_f32_16x16x32_bf16 v[90:93], v[30:33], v[162:165], v[94:97]
	v_exp_f32_e32 v43, v43
	v_cvt_pk_bf16_f32 v3, v60, v61
	ds_read_b128 v[162:165], v115 offset:2048
	s_waitcnt lgkmcnt(12)
	v_mfma_f32_16x16x32_bf16 v[94:97], v[30:33], v[144:147], v[102:105]
	v_exp_f32_e32 v44, v44
	v_cvt_pk_bf16_f32 v4, v54, v55
	v_mfma_f32_16x16x32_bf16 v[58:61], v[34:37], v[144:147], v[98:101]
	v_exp_f32_e32 v45, v45
	v_cvt_pk_bf16_f32 v5, v56, v57
	ds_read_b128 v[144:147], v1 offset:4096
	s_waitcnt lgkmcnt(11)
	v_mfma_f32_16x16x32_bf16 v[120:123], v[34:37], v[166:169], v[136:139]
	v_exp_f32_e32 v46, v46
	v_mfma_f32_16x16x32_bf16 v[124:127], v[30:33], v[166:169], v[140:143]
	v_exp_f32_e32 v47, v47
	ds_read_b128 v[136:139], v115 offset:4096
	s_waitcnt lgkmcnt(10)
	v_mfma_f32_16x16x32_bf16 v[116:119], v[30:33], v[170:173], v[132:135]
	v_exp_f32_e32 v48, v48
	v_mfma_f32_16x16x32_bf16 v[110:113], v[34:37], v[170:173], v[174:177]
	v_exp_f32_e32 v49, v49
	s_nop 1
	ds_read_b128 v[132:135], v1 offset:6144
	s_waitcnt lgkmcnt(9)
	v_mfma_f32_16x16x32_bf16 v[102:105], v[34:37], v[208:211], v[216:219]
	v_exp_f32_e32 v50, v50
	v_mfma_f32_16x16x32_bf16 v[106:109], v[30:33], v[208:211], v[148:151]
	v_exp_f32_e32 v51, v51
	ds_read_b128 v[166:169], v115 offset:6144
	s_waitcnt lgkmcnt(8)
	v_mfma_f32_16x16x32_bf16 v[98:101], v[30:33], v[220:223], v[212:215]
	v_exp_f32_e32 v52, v52
	v_mfma_f32_16x16x32_bf16 v[54:57], v[34:37], v[220:223], v[224:227]
	v_exp_f32_e32 v53, v53
	v_cvt_pk_bf16_f32 v34, v38, v39
	v_cvt_pk_bf16_f32 v35, v40, v41
	v_cvt_pk_bf16_f32 v36, v46, v47
	v_cvt_pk_bf16_f32 v37, v48, v49
	v_cvt_pk_bf16_f32 v30, v42, v43
	v_cvt_pk_bf16_f32 v31, v44, v45
	v_cvt_pk_bf16_f32 v32, v50, v51
	v_cvt_pk_bf16_f32 v33, v52, v53
	s_waitcnt vmcnt(4)
	s_barrier
	ds_read_b64_tr_b16 v[170:171], v203 offset:49152
	ds_read_b64_tr_b16 v[172:173], v203 offset:51200
	s_waitcnt lgkmcnt(9)
	v_mfma_f32_16x16x32_bf16 v[248:251], v[128:131], v[10:13], 0
	s_waitcnt lgkmcnt(8)
	v_mfma_f32_16x16x32_bf16 v[38:41], v[128:131], v[18:21], 0
	ds_read_b64_tr_b16 v[174:175], v204 offset:49152
	ds_read_b64_tr_b16 v[176:177], v204 offset:51200
	v_mfma_f32_16x16x32_bf16 v[50:53], v[152:155], v[14:17], v[248:251]
	v_mfma_f32_16x16x32_bf16 v[42:45], v[152:155], v[22:25], v[38:41]
	ds_read_b64_tr_b16 v[128:129], v205 offset:49152
	ds_read_b64_tr_b16 v[130:131], v205 offset:51200
	s_waitcnt lgkmcnt(11)
	v_mfma_f32_16x16x32_bf16 v[248:251], v[158:161], v[10:13], 0
	s_waitcnt lgkmcnt(10)
	v_mfma_f32_16x16x32_bf16 v[38:41], v[158:161], v[18:21], 0
	ds_read_b64_tr_b16 v[208:209], v206 offset:49152
	ds_read_b64_tr_b16 v[210:211], v206 offset:51200
	v_mfma_f32_16x16x32_bf16 v[46:49], v[162:165], v[14:17], v[248:251]
	v_mfma_f32_16x16x32_bf16 v[38:41], v[162:165], v[22:25], v[38:41]
	ds_read_b64_tr_b16 v[158:159], v203 offset:57344
	ds_read_b64_tr_b16 v[160:161], v203 offset:59392
	s_waitcnt lgkmcnt(13)
	v_mfma_f32_16x16x32_bf16 v[140:143], v[144:147], v[10:13], 0
	s_waitcnt lgkmcnt(12)
	v_mfma_f32_16x16x32_bf16 v[144:147], v[144:147], v[18:21], 0
	ds_read_b64_tr_b16 v[162:163], v204 offset:57344
	ds_read_b64_tr_b16 v[164:165], v204 offset:59392
	v_mfma_f32_16x16x32_bf16 v[140:143], v[136:139], v[14:17], v[140:143]
	v_mfma_f32_16x16x32_bf16 v[144:147], v[136:139], v[22:25], v[144:147]
	ds_read_b64_tr_b16 v[136:137], v205 offset:57344
	ds_read_b64_tr_b16 v[138:139], v205 offset:59392
	s_waitcnt lgkmcnt(14)
	v_mfma_f32_16x16x32_bf16 v[148:151], v[132:135], v[10:13], 0
	v_mfma_f32_16x16x32_bf16 v[132:135], v[132:135], v[18:21], 0
	ds_read_b64_tr_b16 v[212:213], v206 offset:57344
	ds_read_b64_tr_b16 v[214:215], v206 offset:59392
	v_mfma_f32_16x16x32_bf16 v[148:151], v[166:169], v[14:17], v[148:151]
	v_mfma_f32_16x16x32_bf16 v[152:155], v[166:169], v[22:25], v[132:135]
	s_add_u32 s74, s14, 0xfd010000
	s_addc_u32 s75, s15, -1
	s_mov_b32 s76, m0
	s_mov_b32 m0, s66
	s_nop 0
	global_load_lds_dwordx4 v157, s[74:75]
	s_mov_b32 m0, s76
	s_add_u32 s74, s14, 0xfd010080
	s_addc_u32 s75, s15, -1
	s_mov_b32 s76, m0
	s_mov_b32 m0, s28
	s_nop 0
	global_load_lds_dwordx4 v157, s[74:75]
	s_mov_b32 m0, s76
	s_mov_b32 s74, m0
	s_mov_b32 m0, s29
	s_nop 0
	global_load_lds_dwordx4 v156, s[14:15]
	s_mov_b32 m0, s74
	s_add_u32 s74, s14, 0x80
	s_addc_u32 s75, s15, 0
	s_mov_b32 s76, m0
	s_mov_b32 m0, s67
	s_nop 0
	global_load_lds_dwordx4 v156, s[74:75]
	s_mov_b32 m0, s76
	s_nop 0
	ds_read_b64_tr_b16 v[132:133], v203 offset:53248
	ds_read_b64_tr_b16 v[134:135], v203 offset:55296
	v_mfma_f32_16x16x32_bf16 v[66:69], v[6:9], v[26:29], v[66:69]
	v_exp_f32_e32 v50, v50
	s_waitcnt lgkmcnt(14)
	v_mfma_f32_16x16x32_bf16 v[62:65], v[6:9], v[170:173], v[62:65]
	v_mfma_f32_16x16x32_bf16 v[78:81], v[2:5], v[170:173], v[78:81]
	v_exp_f32_e32 v51, v51
	v_mfma_f32_16x16x32_bf16 v[70:73], v[2:5], v[26:29], v[70:73]
	ds_read_b64_tr_b16 v[166:167], v204 offset:53248
	ds_read_b64_tr_b16 v[168:169], v204 offset:55296
	v_mfma_f32_16x16x32_bf16 v[82:85], v[2:5], v[174:177], v[82:85]
	v_exp_f32_e32 v52, v52
	v_mfma_f32_16x16x32_bf16 v[74:77], v[6:9], v[174:177], v[74:77]
	v_exp_f32_e32 v53, v53
	ds_read_b64_tr_b16 v[170:171], v205 offset:53248
	ds_read_b64_tr_b16 v[172:173], v205 offset:55296
	s_waitcnt lgkmcnt(14)
; #define ATT_WAIT_BARV(N) asm volatile("s_waitcnt vmcnt(" #N ")\n\ts_barrier" ::: "memory")
; __device__ __forceinline__ void attn_unit_d16(const UnitDesc& U, char* shm, float lam, const float* subw) {
;     ...
;     for (int t = 1; t <= NT - 4; t += 4) {
;         STEP_D16(t, true, true, true, 1, 2, 0, 0, 3);     ATT_WAIT_BARV(4);
;         STEP_D16(t + 1, true, true, true, 2, 3, 1, 1, 0); ATT_WAIT_BARV(4);
;         STEP_D16(t + 2, true, true, true, 3, 0, 2, 2, 1); ATT_WAIT_BARV(4);
;         STEP_D16(t + 3, true, true, true, 0, 1, 3, 3, 2); ATT_WAIT_BARV(4);
;     }
	v_mfma_f32_16x16x32_bf16 v[86:89], v[6:9], v[128:131], v[86:89]
	v_exp_f32_e32 v42, v42
	v_mfma_f32_16x16x32_bf16 v[128:131], v[2:5], v[128:131], v[90:93]
	v_exp_f32_e32 v43, v43
	ds_read_b64_tr_b16 v[174:175], v206 offset:53248
	ds_read_b64_tr_b16 v[176:177], v206 offset:55296
	v_mfma_f32_16x16x32_bf16 v[58:61], v[6:9], v[208:211], v[58:61]
	v_exp_f32_e32 v44, v44
	s_nop 0
	v_exp_f32_e32 v45, v45
	v_mfma_f32_16x16x32_bf16 v[208:211], v[2:5], v[208:211], v[94:97]
	ds_read_b64_tr_b16 v[216:217], v203 offset:61440
	ds_read_b64_tr_b16 v[218:219], v203 offset:63488
	v_exp_f32_e32 v46, v46
	s_waitcnt lgkmcnt(14)
	v_mfma_f32_16x16x32_bf16 v[220:223], v[6:9], v[158:161], v[120:123]
	s_nop 0
	v_exp_f32_e32 v47, v47
	v_mfma_f32_16x16x32_bf16 v[158:161], v[2:5], v[158:161], v[124:127]
	ds_read_b64_tr_b16 v[224:225], v204 offset:61440
	ds_read_b64_tr_b16 v[226:227], v204 offset:63488
	v_exp_f32_e32 v48, v48
	v_mfma_f32_16x16x32_bf16 v[228:231], v[6:9], v[162:165], v[110:113]
	s_nop 0
	v_exp_f32_e32 v49, v49
	v_mfma_f32_16x16x32_bf16 v[162:165], v[2:5], v[162:165], v[116:119]
	ds_read_b64_tr_b16 v[232:233], v205 offset:61440
	ds_read_b64_tr_b16 v[234:235], v205 offset:63488
	v_exp_f32_e32 v38, v38
	s_waitcnt lgkmcnt(14)
	v_mfma_f32_16x16x32_bf16 v[236:239], v[6:9], v[136:139], v[102:105]
	v_mfma_f32_16x16x32_bf16 v[136:139], v[2:5], v[136:139], v[106:109]
	v_exp_f32_e32 v39, v39
	ds_read_b64_tr_b16 v[240:241], v206 offset:61440
	ds_read_b64_tr_b16 v[242:243], v206 offset:63488
	v_exp_f32_e32 v40, v40
	v_mfma_f32_16x16x32_bf16 v[244:247], v[6:9], v[212:215], v[54:57]
	s_nop 0
	v_exp_f32_e32 v41, v41
	v_mfma_f32_16x16x32_bf16 v[212:215], v[2:5], v[212:215], v[98:101]
	ds_read_b128 v[110:113], v1 offset:16384
	v_mfma_f32_16x16x32_bf16 v[106:109], v[34:37], v[26:29], v[66:69]
	v_exp_f32_e32 v140, v140
	v_cvt_pk_bf16_f32 v6, v50, v51
	s_waitcnt lgkmcnt(14)
	v_mfma_f32_16x16x32_bf16 v[98:101], v[34:37], v[132:135], v[62:65]
	v_mfma_f32_16x16x32_bf16 v[90:93], v[30:33], v[132:135], v[78:81]
	v_exp_f32_e32 v141, v141
	v_cvt_pk_bf16_f32 v7, v52, v53
	v_mfma_f32_16x16x32_bf16 v[102:105], v[30:33], v[26:29], v[70:73]
	ds_read_b128 v[26:29], v115 offset:16384
	s_waitcnt lgkmcnt(14)
	v_mfma_f32_16x16x32_bf16 v[82:85], v[30:33], v[166:169], v[82:85]
	v_exp_f32_e32 v142, v142
	v_cvt_pk_bf16_f32 v8, v46, v47
	v_mfma_f32_16x16x32_bf16 v[94:97], v[34:37], v[166:169], v[74:77]
	v_exp_f32_e32 v143, v143
	v_cvt_pk_bf16_f32 v9, v48, v49
	ds_read_b128 v[116:119], v1 offset:18432
	s_waitcnt lgkmcnt(13)
	v_mfma_f32_16x16x32_bf16 v[86:89], v[34:37], v[170:173], v[86:89]
	v_exp_f32_e32 v144, v144
	v_cvt_pk_bf16_f32 v2, v42, v43
	v_mfma_f32_16x16x32_bf16 v[74:77], v[30:33], v[170:173], v[128:131]
	v_exp_f32_e32 v145, v145
	v_cvt_pk_bf16_f32 v3, v44, v45
	ds_read_b128 v[120:123], v115 offset:18432
	s_waitcnt lgkmcnt(12)
	v_mfma_f32_16x16x32_bf16 v[66:69], v[30:33], v[174:177], v[208:211]
	v_exp_f32_e32 v146, v146
	v_cvt_pk_bf16_f32 v4, v38, v39
	v_mfma_f32_16x16x32_bf16 v[78:81], v[34:37], v[174:177], v[58:61]
	v_exp_f32_e32 v147, v147
	v_cvt_pk_bf16_f32 v5, v40, v41
	ds_read_b128 v[124:127], v1 offset:20480
	s_waitcnt lgkmcnt(11)
	v_mfma_f32_16x16x32_bf16 v[70:73], v[34:37], v[216:219], v[220:223]
	v_exp_f32_e32 v148, v148
	v_mfma_f32_16x16x32_bf16 v[58:61], v[30:33], v[216:219], v[158:161]
	v_exp_f32_e32 v149, v149
	ds_read_b128 v[132:135], v115 offset:20480
	s_waitcnt lgkmcnt(10)
	v_mfma_f32_16x16x32_bf16 v[50:53], v[30:33], v[224:227], v[162:165]
	v_exp_f32_e32 v150, v150
	v_mfma_f32_16x16x32_bf16 v[62:65], v[34:37], v[224:227], v[228:231]
	v_exp_f32_e32 v151, v151
	ds_read_b128 v[128:131], v1 offset:22528
	s_waitcnt lgkmcnt(9)
	v_mfma_f32_16x16x32_bf16 v[54:57], v[34:37], v[232:235], v[236:239]
	v_exp_f32_e32 v152, v152
	v_mfma_f32_16x16x32_bf16 v[42:45], v[30:33], v[232:235], v[136:139]
	v_exp_f32_e32 v153, v153
	s_nop 1
	ds_read_b128 v[136:139], v115 offset:22528
	s_waitcnt lgkmcnt(8)
	v_mfma_f32_16x16x32_bf16 v[38:41], v[30:33], v[240:243], v[212:215]
	v_exp_f32_e32 v154, v154
	v_mfma_f32_16x16x32_bf16 v[46:49], v[34:37], v[240:243], v[244:247]
	v_exp_f32_e32 v155, v155
	v_cvt_pk_bf16_f32 v34, v140, v141
	v_cvt_pk_bf16_f32 v35, v142, v143
	v_cvt_pk_bf16_f32 v36, v148, v149
	v_cvt_pk_bf16_f32 v37, v150, v151
	v_cvt_pk_bf16_f32 v30, v144, v145
	v_cvt_pk_bf16_f32 v31, v146, v147
	v_cvt_pk_bf16_f32 v32, v152, v153
	v_cvt_pk_bf16_f32 v33, v154, v155
	s_add_i32 s33, s33, 4
	s_add_u32 s14, s14, 0x40000
	s_waitcnt vmcnt(4)
	s_barrier
	s_addc_u32 s15, s15, 0
	s_cmpk_gt_u32 s33, 0x78
	s_cbranch_scc0 .LBB0_444
; #define ATT_WAIT_BAR(N) asm volatile("s_waitcnt vmcnt(" #N ") lgkmcnt(0)\n\ts_barrier" ::: "memory")
; __device__ __forceinline__ void attn_unit_d16(const UnitDesc& U, char* shm, float lam, const float* subw) {
;     ...
;     STEP_D16(NT - 3, false, true, true, 1, 2, 0, 0, 3);   ATT_WAIT_BAR(2);
	ds_read_b64_tr_b16 v[158:159], v203
	ds_read_b64_tr_b16 v[160:161], v203 offset:2048
	s_waitcnt lgkmcnt(9)
	v_mfma_f32_16x16x32_bf16 v[140:143], v[110:113], v[10:13], 0
	s_waitcnt lgkmcnt(8)
	v_mfma_f32_16x16x32_bf16 v[152:155], v[26:29], v[14:17], v[140:143]
	ds_read_b64_tr_b16 v[162:163], v204
	ds_read_b64_tr_b16 v[164:165], v204 offset:2048
	v_mfma_f32_16x16x32_bf16 v[110:113], v[110:113], v[18:21], 0
	v_mfma_f32_16x16x32_bf16 v[144:147], v[26:29], v[22:25], v[110:113]
	ds_read_b64_tr_b16 v[166:167], v205
	ds_read_b64_tr_b16 v[168:169], v205 offset:2048
	s_waitcnt lgkmcnt(11)
	v_mfma_f32_16x16x32_bf16 v[26:29], v[116:119], v[10:13], 0
	s_waitcnt lgkmcnt(10)
	v_mfma_f32_16x16x32_bf16 v[148:151], v[120:123], v[14:17], v[26:29]
	ds_read_b64_tr_b16 v[170:171], v206
	ds_read_b64_tr_b16 v[172:173], v206 offset:2048
	v_mfma_f32_16x16x32_bf16 v[26:29], v[116:119], v[18:21], 0
	v_mfma_f32_16x16x32_bf16 v[140:143], v[120:123], v[22:25], v[26:29]
	ds_read_b64_tr_b16 v[174:175], v203 offset:8192
	ds_read_b64_tr_b16 v[176:177], v203 offset:10240
	s_waitcnt lgkmcnt(13)
	v_mfma_f32_16x16x32_bf16 v[26:29], v[124:127], v[10:13], 0
	s_waitcnt lgkmcnt(12)
	v_mfma_f32_16x16x32_bf16 v[110:113], v[132:135], v[14:17], v[26:29]
	ds_read_b64_tr_b16 v[208:209], v204 offset:8192
	ds_read_b64_tr_b16 v[210:211], v204 offset:10240
	v_mfma_f32_16x16x32_bf16 v[26:29], v[124:127], v[18:21], 0
	v_mfma_f32_16x16x32_bf16 v[116:119], v[132:135], v[22:25], v[26:29]
	ds_read_b64_tr_b16 v[132:133], v205 offset:8192
	ds_read_b64_tr_b16 v[134:135], v205 offset:10240
	s_waitcnt lgkmcnt(14)
	v_mfma_f32_16x16x32_bf16 v[26:29], v[128:131], v[10:13], 0
	v_mfma_f32_16x16x32_bf16 v[120:123], v[136:139], v[14:17], v[26:29]
	ds_read_b64_tr_b16 v[212:213], v206 offset:8192
	ds_read_b64_tr_b16 v[214:215], v206 offset:10240
	v_mfma_f32_16x16x32_bf16 v[26:29], v[128:131], v[18:21], 0
	v_mfma_f32_16x16x32_bf16 v[124:127], v[136:139], v[22:25], v[26:29]
	s_add_u32 s14, s10, 0x7f0000
	s_addc_u32 s15, s11, 0
	s_mov_b32 s28, m0
	s_mov_b32 m0, s68
	s_nop 0
	global_load_lds_dwordx4 v156, s[14:15]
	s_mov_b32 m0, s28
	s_add_u32 s10, s10, 0x7f0080
	s_addc_u32 s11, s11, 0
	s_mov_b32 s14, m0
	s_mov_b32 m0, s69
	s_nop 0
	global_load_lds_dwordx4 v156, s[10:11]
	s_mov_b32 m0, s14
	ds_read_b64_tr_b16 v[128:129], v203 offset:4096
	ds_read_b64_tr_b16 v[130:131], v203 offset:6144
	s_nop 0
	v_mov_b64_e32 v[28:29], s[6:7]
	v_mov_b64_e32 v[26:27], s[4:5]
	v_exp_f32_e32 v152, v152
	s_waitcnt lgkmcnt(14)
	v_mfma_f32_16x16x32_bf16 v[98:101], v[6:9], v[158:161], v[98:101]
	v_mfma_f32_16x16x32_bf16 v[106:109], v[6:9], v[26:29], v[106:109]
	v_exp_f32_e32 v153, v153
	v_mfma_f32_16x16x32_bf16 v[102:105], v[2:5], v[26:29], v[102:105]
	v_mfma_f32_16x16x32_bf16 v[90:93], v[2:5], v[158:161], v[90:93]
	ds_read_b64_tr_b16 v[136:137], v204 offset:4096
	ds_read_b64_tr_b16 v[138:139], v204 offset:6144
	v_exp_f32_e32 v154, v154
	v_mfma_f32_16x16x32_bf16 v[94:97], v[6:9], v[162:165], v[94:97]
	v_mfma_f32_16x16x32_bf16 v[82:85], v[2:5], v[162:165], v[82:85]
	v_exp_f32_e32 v155, v155
	ds_read_b64_tr_b16 v[156:157], v205 offset:4096
	ds_read_b64_tr_b16 v[158:159], v205 offset:6144
	v_exp_f32_e32 v144, v144
	s_waitcnt lgkmcnt(14)
	v_mfma_f32_16x16x32_bf16 v[86:89], v[6:9], v[166:169], v[86:89]
	s_nop 0
	v_exp_f32_e32 v145, v145
	v_mfma_f32_16x16x32_bf16 v[160:163], v[2:5], v[166:169], v[74:77]
	ds_read_b64_tr_b16 v[164:165], v206 offset:4096
	ds_read_b64_tr_b16 v[166:167], v206 offset:6144
	v_exp_f32_e32 v146, v146
	v_mfma_f32_16x16x32_bf16 v[216:219], v[6:9], v[170:173], v[78:81]
	s_nop 0
	v_exp_f32_e32 v147, v147
	v_mfma_f32_16x16x32_bf16 v[168:171], v[2:5], v[170:173], v[66:69]
	ds_read_b64_tr_b16 v[220:221], v203 offset:12288
	ds_read_b64_tr_b16 v[222:223], v203 offset:14336
	v_exp_f32_e32 v148, v148
	s_waitcnt lgkmcnt(14)
	v_mfma_f32_16x16x32_bf16 v[224:227], v[6:9], v[174:177], v[70:73]
	v_mfma_f32_16x16x32_bf16 v[58:61], v[2:5], v[174:177], v[58:61]
	v_exp_f32_e32 v149, v149
	ds_read_b64_tr_b16 v[172:173], v204 offset:12288
	ds_read_b64_tr_b16 v[174:175], v204 offset:14336
	v_exp_f32_e32 v150, v150
	v_mfma_f32_16x16x32_bf16 v[176:179], v[6:9], v[208:211], v[62:65]
	v_mfma_f32_16x16x32_bf16 v[50:53], v[2:5], v[208:211], v[50:53]
	v_exp_f32_e32 v151, v151
	ds_read_b64_tr_b16 v[208:209], v205 offset:12288
	ds_read_b64_tr_b16 v[210:211], v205 offset:14336
	s_waitcnt lgkmcnt(14)
	v_mfma_f32_16x16x32_bf16 v[54:57], v[6:9], v[132:135], v[54:57]
	v_exp_f32_e32 v140, v140
	v_mfma_f32_16x16x32_bf16 v[42:45], v[2:5], v[132:135], v[42:45]
	v_exp_f32_e32 v141, v141
	ds_read_b64_tr_b16 v[228:229], v206 offset:12288
	ds_read_b64_tr_b16 v[230:231], v206 offset:14336
	v_mfma_f32_16x16x32_bf16 v[46:49], v[6:9], v[212:215], v[46:49]
	v_exp_f32_e32 v142, v142
	s_nop 0
	v_exp_f32_e32 v143, v143
	v_mfma_f32_16x16x32_bf16 v[212:215], v[2:5], v[212:215], v[38:41]
	s_nop 2
	ds_read_b128 v[38:41], v1 offset:32768
	v_mfma_f32_16x16x32_bf16 v[66:69], v[34:37], v[26:29], v[106:109]
	v_exp_f32_e32 v110, v110
	v_cvt_pk_bf16_f32 v6, v152, v153
	s_waitcnt lgkmcnt(14)
	v_mfma_f32_16x16x32_bf16 v[62:65], v[34:37], v[128:131], v[98:101]
	v_mfma_f32_16x16x32_bf16 v[70:73], v[30:33], v[26:29], v[102:105]
	v_exp_f32_e32 v111, v111
	v_cvt_pk_bf16_f32 v7, v154, v155
	v_mfma_f32_16x16x32_bf16 v[78:81], v[30:33], v[128:131], v[90:93]
	ds_read_b128 v[232:235], v115 offset:32768
	s_waitcnt lgkmcnt(14)
	v_mfma_f32_16x16x32_bf16 v[74:77], v[34:37], v[136:139], v[94:97]
	v_exp_f32_e32 v112, v112
	v_cvt_pk_bf16_f32 v8, v148, v149
	v_mfma_f32_16x16x32_bf16 v[82:85], v[30:33], v[136:139], v[82:85]
	v_exp_f32_e32 v113, v113
	v_cvt_pk_bf16_f32 v9, v150, v151
	ds_read_b128 v[236:239], v1 offset:34816
	v_exp_f32_e32 v116, v116
	v_cvt_pk_bf16_f32 v2, v144, v145
	s_waitcnt lgkmcnt(13)
; #define ATT_WAIT_BAR(N) asm volatile("s_waitcnt vmcnt(" #N ") lgkmcnt(0)\n\ts_barrier" ::: "memory")
; __device__ __forceinline__ void attn_unit_d16(const UnitDesc& U, char* shm, float lam, const float* subw) {
;     ...
;     STEP_D16(NT - 3, false, true, true, 1, 2, 0, 0, 3);   ATT_WAIT_BAR(2);
;     STEP_D16(NT - 2, false, false, true, 2, 3, 1, 1, 0);  ATT_WAIT_BAR(0);
	v_mfma_f32_16x16x32_bf16 v[90:93], v[34:37], v[156:159], v[86:89]
	s_nop 0
	v_exp_f32_e32 v117, v117
	v_cvt_pk_bf16_f32 v3, v146, v147
	v_mfma_f32_16x16x32_bf16 v[94:97], v[30:33], v[156:159], v[160:163]
	ds_read_b128 v[156:159], v115 offset:34816
	v_exp_f32_e32 v118, v118
	v_cvt_pk_bf16_f32 v4, v140, v141
	s_waitcnt lgkmcnt(12)
	v_mfma_f32_16x16x32_bf16 v[98:101], v[34:37], v[164:167], v[216:219]
	s_nop 0
	v_exp_f32_e32 v119, v119
	v_cvt_pk_bf16_f32 v5, v142, v143
	v_mfma_f32_16x16x32_bf16 v[102:105], v[30:33], v[164:167], v[168:171]
	ds_read_b128 v[160:163], v1 offset:36864
	v_exp_f32_e32 v120, v120
	s_waitcnt lgkmcnt(11)
	v_mfma_f32_16x16x32_bf16 v[148:151], v[34:37], v[220:223], v[224:227]
	s_nop 0
	v_exp_f32_e32 v121, v121
	v_mfma_f32_16x16x32_bf16 v[152:155], v[30:33], v[220:223], v[58:61]
	ds_read_b128 v[164:167], v115 offset:36864
	v_exp_f32_e32 v122, v122
	s_waitcnt lgkmcnt(10)
	v_mfma_f32_16x16x32_bf16 v[140:143], v[34:37], v[172:175], v[176:179]
	s_nop 0
	v_exp_f32_e32 v123, v123
	v_mfma_f32_16x16x32_bf16 v[144:147], v[30:33], v[172:175], v[50:53]
	s_nop 2
	ds_read_b128 v[50:53], v1 offset:38912
	v_exp_f32_e32 v124, v124
	s_waitcnt lgkmcnt(9)
	v_mfma_f32_16x16x32_bf16 v[132:135], v[34:37], v[208:211], v[54:57]
	s_nop 0
	v_exp_f32_e32 v125, v125
	v_mfma_f32_16x16x32_bf16 v[136:139], v[30:33], v[208:211], v[42:45]
	ds_read_b128 v[168:171], v115 offset:38912
	v_exp_f32_e32 v126, v126
	s_waitcnt lgkmcnt(8)
	v_mfma_f32_16x16x32_bf16 v[106:109], v[34:37], v[228:231], v[46:49]
	s_nop 0
	v_exp_f32_e32 v127, v127
	v_mfma_f32_16x16x32_bf16 v[128:131], v[30:33], v[228:231], v[212:215]
	v_cvt_pk_bf16_f32 v34, v110, v111
	v_cvt_pk_bf16_f32 v35, v112, v113
	v_cvt_pk_bf16_f32 v36, v120, v121
	v_cvt_pk_bf16_f32 v37, v122, v123
	v_cvt_pk_bf16_f32 v30, v116, v117
	v_cvt_pk_bf16_f32 v31, v118, v119
	v_cvt_pk_bf16_f32 v32, v124, v125
	v_cvt_pk_bf16_f32 v33, v126, v127
	s_waitcnt vmcnt(2) lgkmcnt(0)
	s_barrier
	ds_read_b64_tr_b16 v[116:117], v203 offset:16384
	ds_read_b64_tr_b16 v[118:119], v203 offset:18432
	s_waitcnt lgkmcnt(9)
	v_mfma_f32_16x16x32_bf16 v[42:45], v[38:41], v[10:13], 0
	s_waitcnt lgkmcnt(8)
	v_mfma_f32_16x16x32_bf16 v[110:113], v[232:235], v[14:17], v[42:45]
	ds_read_b64_tr_b16 v[120:121], v204 offset:16384
	ds_read_b64_tr_b16 v[122:123], v204 offset:18432
	v_mfma_f32_16x16x32_bf16 v[38:41], v[38:41], v[18:21], 0
	v_mfma_f32_16x16x32_bf16 v[58:61], v[232:235], v[22:25], v[38:41]
	ds_read_b64_tr_b16 v[124:125], v205 offset:16384
	ds_read_b64_tr_b16 v[126:127], v205 offset:18432
	s_waitcnt lgkmcnt(11)
	v_mfma_f32_16x16x32_bf16 v[38:41], v[236:239], v[10:13], 0
	s_waitcnt lgkmcnt(10)
	v_mfma_f32_16x16x32_bf16 v[86:89], v[156:159], v[14:17], v[38:41]
	ds_read_b64_tr_b16 v[172:173], v206 offset:16384
	ds_read_b64_tr_b16 v[174:175], v206 offset:18432
	v_mfma_f32_16x16x32_bf16 v[38:41], v[236:239], v[18:21], 0
	v_mfma_f32_16x16x32_bf16 v[54:57], v[156:159], v[22:25], v[38:41]
	ds_read_b64_tr_b16 v[156:157], v203 offset:24576
	ds_read_b64_tr_b16 v[158:159], v203 offset:26624
	s_waitcnt lgkmcnt(13)
	v_mfma_f32_16x16x32_bf16 v[38:41], v[160:163], v[10:13], 0
	s_waitcnt lgkmcnt(12)
	v_mfma_f32_16x16x32_bf16 v[38:41], v[164:167], v[14:17], v[38:41]
	ds_read_b64_tr_b16 v[176:177], v204 offset:24576
	ds_read_b64_tr_b16 v[178:179], v204 offset:26624
	v_mfma_f32_16x16x32_bf16 v[42:45], v[160:163], v[18:21], 0
	v_mfma_f32_16x16x32_bf16 v[42:45], v[164:167], v[22:25], v[42:45]
	ds_read_b64_tr_b16 v[160:161], v205 offset:24576
	ds_read_b64_tr_b16 v[162:163], v205 offset:26624
	s_waitcnt lgkmcnt(14)
	v_mfma_f32_16x16x32_bf16 v[46:49], v[50:53], v[10:13], 0
	v_mfma_f32_16x16x32_bf16 v[46:49], v[168:171], v[14:17], v[46:49]
	ds_read_b64_tr_b16 v[164:165], v206 offset:24576
	ds_read_b64_tr_b16 v[166:167], v206 offset:26624
	v_mfma_f32_16x16x32_bf16 v[50:53], v[50:53], v[18:21], 0
	v_mfma_f32_16x16x32_bf16 v[50:53], v[168:171], v[22:25], v[50:53]
	ds_read_b64_tr_b16 v[168:169], v203 offset:20480
	ds_read_b64_tr_b16 v[170:171], v203 offset:22528
	v_mfma_f32_16x16x32_bf16 v[66:69], v[6:9], v[26:29], v[66:69]
	v_exp_f32_e32 v110, v110
	s_waitcnt lgkmcnt(14)
	v_mfma_f32_16x16x32_bf16 v[62:65], v[6:9], v[116:119], v[62:65]
	v_mfma_f32_16x16x32_bf16 v[70:73], v[2:5], v[26:29], v[70:73]
	v_exp_f32_e32 v111, v111
	v_mfma_f32_16x16x32_bf16 v[78:81], v[2:5], v[116:119], v[78:81]
	ds_read_b64_tr_b16 v[116:117], v204 offset:20480
	ds_read_b64_tr_b16 v[118:119], v204 offset:22528
	v_mfma_f32_16x16x32_bf16 v[74:77], v[6:9], v[120:123], v[74:77]
	v_exp_f32_e32 v112, v112
	v_mfma_f32_16x16x32_bf16 v[82:85], v[2:5], v[120:123], v[82:85]
	v_exp_f32_e32 v113, v113
	ds_read_b64_tr_b16 v[120:121], v205 offset:20480
	ds_read_b64_tr_b16 v[122:123], v205 offset:22528
	v_exp_f32_e32 v58, v58
	s_waitcnt lgkmcnt(14)
	v_mfma_f32_16x16x32_bf16 v[90:93], v[6:9], v[124:127], v[90:93]
	s_nop 0
	v_exp_f32_e32 v59, v59
	v_mfma_f32_16x16x32_bf16 v[94:97], v[2:5], v[124:127], v[94:97]
	ds_read_b64_tr_b16 v[124:125], v206 offset:20480
	ds_read_b64_tr_b16 v[126:127], v206 offset:22528
	v_exp_f32_e32 v60, v60
	v_mfma_f32_16x16x32_bf16 v[98:101], v[6:9], v[172:175], v[98:101]
	s_nop 0
	v_exp_f32_e32 v61, v61
	v_mfma_f32_16x16x32_bf16 v[102:105], v[2:5], v[172:175], v[102:105]
	ds_read_b64_tr_b16 v[172:173], v203 offset:28672
	ds_read_b64_tr_b16 v[174:175], v203 offset:30720
	v_exp_f32_e32 v86, v86
	s_waitcnt lgkmcnt(14)
; #define ATT_WAIT_BAR(N) asm volatile("s_waitcnt vmcnt(" #N ") lgkmcnt(0)\n\ts_barrier" ::: "memory")
; __device__ __forceinline__ void attn_unit_d16(const UnitDesc& U, char* shm, float lam, const float* subw) {
;     ...
;     STEP_D16(NT - 2, false, false, true, 2, 3, 1, 1, 0);  ATT_WAIT_BAR(0);
;     STEP_D16(NT - 1, false, false, false, 3, 0, 2, 2, 1); ATT_WAIT_BAR(0);
	v_mfma_f32_16x16x32_bf16 v[148:151], v[6:9], v[156:159], v[148:151]
	s_nop 0
	v_exp_f32_e32 v87, v87
	v_mfma_f32_16x16x32_bf16 v[152:155], v[2:5], v[156:159], v[152:155]
	ds_read_b64_tr_b16 v[156:157], v204 offset:28672
	ds_read_b64_tr_b16 v[158:159], v204 offset:30720
	v_exp_f32_e32 v88, v88
	v_mfma_f32_16x16x32_bf16 v[140:143], v[6:9], v[176:179], v[140:143]
	s_nop 0
	v_exp_f32_e32 v89, v89
	v_mfma_f32_16x16x32_bf16 v[144:147], v[2:5], v[176:179], v[144:147]
	ds_read_b64_tr_b16 v[176:177], v205 offset:28672
	ds_read_b64_tr_b16 v[178:179], v205 offset:30720
	v_exp_f32_e32 v54, v54
	s_waitcnt lgkmcnt(14)
	v_mfma_f32_16x16x32_bf16 v[208:211], v[6:9], v[160:163], v[132:135]
	s_nop 0
	v_exp_f32_e32 v55, v55
	v_mfma_f32_16x16x32_bf16 v[160:163], v[2:5], v[160:163], v[136:139]
	ds_read_b64_tr_b16 v[212:213], v206 offset:28672
	ds_read_b64_tr_b16 v[214:215], v206 offset:30720
	v_exp_f32_e32 v56, v56
	v_mfma_f32_16x16x32_bf16 v[216:219], v[6:9], v[164:167], v[106:109]
	s_nop 0
	v_exp_f32_e32 v57, v57
	v_mfma_f32_16x16x32_bf16 v[164:167], v[2:5], v[164:167], v[128:131]
	ds_read_b128 v[136:139], v1 offset:49152
	v_mfma_f32_16x16x32_bf16 v[66:69], v[34:37], v[26:29], v[66:69]
	v_exp_f32_e32 v38, v38
	v_cvt_pk_bf16_f32 v6, v110, v111
	s_waitcnt lgkmcnt(14)
	v_mfma_f32_16x16x32_bf16 v[62:65], v[34:37], v[168:171], v[62:65]
	v_mfma_f32_16x16x32_bf16 v[70:73], v[30:33], v[26:29], v[70:73]
	v_exp_f32_e32 v39, v39
	v_cvt_pk_bf16_f32 v7, v112, v113
	v_mfma_f32_16x16x32_bf16 v[78:81], v[30:33], v[168:171], v[78:81]
	ds_read_b128 v[168:171], v115 offset:49152
	s_waitcnt lgkmcnt(14)
	v_mfma_f32_16x16x32_bf16 v[74:77], v[34:37], v[116:119], v[74:77]
	v_exp_f32_e32 v40, v40
	v_cvt_pk_bf16_f32 v8, v86, v87
	v_mfma_f32_16x16x32_bf16 v[82:85], v[30:33], v[116:119], v[82:85]
	v_exp_f32_e32 v41, v41
	v_cvt_pk_bf16_f32 v9, v88, v89
	ds_read_b128 v[220:223], v1 offset:51200
	v_exp_f32_e32 v42, v42
	v_cvt_pk_bf16_f32 v2, v58, v59
	s_waitcnt lgkmcnt(13)
	v_mfma_f32_16x16x32_bf16 v[86:89], v[34:37], v[120:123], v[90:93]
	s_nop 0
	v_exp_f32_e32 v43, v43
	v_cvt_pk_bf16_f32 v3, v60, v61
	v_mfma_f32_16x16x32_bf16 v[90:93], v[30:33], v[120:123], v[94:97]
	ds_read_b128 v[224:227], v115 offset:51200
	s_waitcnt lgkmcnt(12)
	v_mfma_f32_16x16x32_bf16 v[58:61], v[34:37], v[124:127], v[98:101]
	v_exp_f32_e32 v44, v44
	v_cvt_pk_bf16_f32 v4, v54, v55
	s_nop 0
	v_exp_f32_e32 v45, v45
	v_cvt_pk_bf16_f32 v5, v56, v57
	v_mfma_f32_16x16x32_bf16 v[94:97], v[30:33], v[124:127], v[102:105]
	ds_read_b128 v[228:231], v1 offset:53248
	v_exp_f32_e32 v46, v46
	s_waitcnt lgkmcnt(11)
	v_mfma_f32_16x16x32_bf16 v[128:131], v[34:37], v[172:175], v[148:151]
	s_nop 0
	v_exp_f32_e32 v47, v47
	v_mfma_f32_16x16x32_bf16 v[132:135], v[30:33], v[172:175], v[152:155]
	ds_read_b128 v[148:151], v115 offset:53248
	v_exp_f32_e32 v48, v48
	s_waitcnt lgkmcnt(10)
	v_mfma_f32_16x16x32_bf16 v[120:123], v[34:37], v[156:159], v[140:143]
	s_nop 0
	v_exp_f32_e32 v49, v49
	v_mfma_f32_16x16x32_bf16 v[124:127], v[30:33], v[156:159], v[144:147]
	ds_read_b128 v[140:143], v1 offset:55296
	v_exp_f32_e32 v50, v50
	s_waitcnt lgkmcnt(9)
	v_mfma_f32_16x16x32_bf16 v[106:109], v[34:37], v[176:179], v[208:211]
	s_nop 0
	v_exp_f32_e32 v51, v51
	v_mfma_f32_16x16x32_bf16 v[110:113], v[30:33], v[176:179], v[160:163]
	ds_read_b128 v[144:147], v115 offset:55296
	v_exp_f32_e32 v52, v52
	s_waitcnt lgkmcnt(8)
	v_mfma_f32_16x16x32_bf16 v[98:101], v[34:37], v[212:215], v[216:219]
	s_nop 0
	v_exp_f32_e32 v53, v53
	v_mfma_f32_16x16x32_bf16 v[102:105], v[30:33], v[212:215], v[164:167]
	v_cvt_pk_bf16_f32 v34, v38, v39
	v_cvt_pk_bf16_f32 v35, v40, v41
	v_cvt_pk_bf16_f32 v36, v46, v47
	v_cvt_pk_bf16_f32 v37, v48, v49
	v_cvt_pk_bf16_f32 v30, v42, v43
	v_cvt_pk_bf16_f32 v31, v44, v45
	v_cvt_pk_bf16_f32 v32, v50, v51
	v_cvt_pk_bf16_f32 v33, v52, v53
	s_waitcnt vmcnt(0) lgkmcnt(0)
	s_barrier
	ds_read_b64_tr_b16 v[152:153], v203 offset:32768
	ds_read_b64_tr_b16 v[154:155], v203 offset:34816
	s_waitcnt lgkmcnt(9)
	v_mfma_f32_16x16x32_bf16 v[38:41], v[136:139], v[10:13], 0
	s_waitcnt lgkmcnt(8)
	v_mfma_f32_16x16x32_bf16 v[116:119], v[168:171], v[14:17], v[38:41]
	ds_read_b64_tr_b16 v[156:157], v204 offset:32768
	ds_read_b64_tr_b16 v[158:159], v204 offset:34816
	v_mfma_f32_16x16x32_bf16 v[38:41], v[136:139], v[18:21], 0
	v_mfma_f32_16x16x32_bf16 v[50:53], v[168:171], v[22:25], v[38:41]
	ds_read_b64_tr_b16 v[136:137], v205 offset:32768
	ds_read_b64_tr_b16 v[138:139], v205 offset:34816
	s_waitcnt lgkmcnt(11)
	v_mfma_f32_16x16x32_bf16 v[38:41], v[220:223], v[10:13], 0
	s_waitcnt lgkmcnt(10)
	v_mfma_f32_16x16x32_bf16 v[54:57], v[224:227], v[14:17], v[38:41]
	ds_read_b64_tr_b16 v[160:161], v206 offset:32768
	ds_read_b64_tr_b16 v[162:163], v206 offset:34816
	v_mfma_f32_16x16x32_bf16 v[38:41], v[220:223], v[18:21], 0
	v_mfma_f32_16x16x32_bf16 v[46:49], v[224:227], v[22:25], v[38:41]
	ds_read_b64_tr_b16 v[164:165], v203 offset:40960
	ds_read_b64_tr_b16 v[166:167], v203 offset:43008
	s_waitcnt lgkmcnt(13)
	v_mfma_f32_16x16x32_bf16 v[38:41], v[228:231], v[10:13], 0
	s_waitcnt lgkmcnt(12)
	v_mfma_f32_16x16x32_bf16 v[38:41], v[148:151], v[14:17], v[38:41]
	ds_read_b64_tr_b16 v[168:169], v204 offset:40960
	ds_read_b64_tr_b16 v[170:171], v204 offset:43008
	v_mfma_f32_16x16x32_bf16 v[42:45], v[228:231], v[18:21], 0
	v_mfma_f32_16x16x32_bf16 v[42:45], v[148:151], v[22:25], v[42:45]
	ds_read_b64_tr_b16 v[148:149], v205 offset:40960
	ds_read_b64_tr_b16 v[150:151], v205 offset:43008
	s_waitcnt lgkmcnt(14)
; #define ATT_WAIT_BAR(N) asm volatile("s_waitcnt vmcnt(" #N ") lgkmcnt(0)\n\ts_barrier" ::: "memory")
; __device__ __forceinline__ void attn_unit_d16(const UnitDesc& U, char* shm, float lam, const float* subw) {
;     ...
;     STEP_D16(NT - 1, false, false, false, 3, 0, 2, 2, 1); ATT_WAIT_BAR(0);
	v_mfma_f32_16x16x32_bf16 v[10:13], v[140:143], v[10:13], 0
	v_mfma_f32_16x16x32_bf16 v[10:13], v[144:147], v[14:17], v[10:13]
	ds_read_b64_tr_b16 v[172:173], v206 offset:40960
	ds_read_b64_tr_b16 v[174:175], v206 offset:43008
	v_mfma_f32_16x16x32_bf16 v[14:17], v[140:143], v[18:21], 0
	v_mfma_f32_16x16x32_bf16 v[14:17], v[144:147], v[22:25], v[14:17]
	ds_read_b64_tr_b16 v[140:141], v203 offset:36864
	ds_read_b64_tr_b16 v[142:143], v203 offset:38912
	v_mfma_f32_16x16x32_bf16 v[18:21], v[6:9], v[26:29], v[66:69]
	v_exp_f32_e32 v116, v116
	s_waitcnt lgkmcnt(14)
	v_mfma_f32_16x16x32_bf16 v[22:25], v[6:9], v[152:155], v[62:65]
	v_mfma_f32_16x16x32_bf16 v[62:65], v[2:5], v[26:29], v[70:73]
	v_exp_f32_e32 v117, v117
	v_mfma_f32_16x16x32_bf16 v[66:69], v[2:5], v[152:155], v[78:81]
	s_nop 0
	ds_read_b64_tr_b16 v[70:71], v204 offset:36864
	ds_read_b64_tr_b16 v[72:73], v204 offset:38912
	v_mfma_f32_16x16x32_bf16 v[74:77], v[6:9], v[156:159], v[74:77]
	v_exp_f32_e32 v118, v118
	v_mfma_f32_16x16x32_bf16 v[78:81], v[2:5], v[156:159], v[82:85]
	v_exp_f32_e32 v119, v119
	s_nop 1
	ds_read_b64_tr_b16 v[82:83], v205 offset:36864
	ds_read_b64_tr_b16 v[84:85], v205 offset:38912
	v_exp_f32_e32 v50, v50
	s_waitcnt lgkmcnt(14)
	v_mfma_f32_16x16x32_bf16 v[86:89], v[6:9], v[136:139], v[86:89]
	s_nop 0
	v_exp_f32_e32 v51, v51
	v_mfma_f32_16x16x32_bf16 v[90:93], v[2:5], v[136:139], v[90:93]
	ds_read_b64_tr_b16 v[136:137], v206 offset:36864
	ds_read_b64_tr_b16 v[138:139], v206 offset:38912
	v_exp_f32_e32 v52, v52
	v_mfma_f32_16x16x32_bf16 v[144:147], v[6:9], v[160:163], v[58:61]
	s_nop 0
	v_exp_f32_e32 v53, v53
	v_mfma_f32_16x16x32_bf16 v[94:97], v[2:5], v[160:163], v[94:97]
	ds_read_b64_tr_b16 v[152:153], v203 offset:45056
	ds_read_b64_tr_b16 v[154:155], v203 offset:47104
	v_exp_f32_e32 v54, v54
	s_waitcnt lgkmcnt(14)
	v_mfma_f32_16x16x32_bf16 v[128:131], v[6:9], v[164:167], v[128:131]
	s_nop 0
	v_exp_f32_e32 v55, v55
	v_mfma_f32_16x16x32_bf16 v[132:135], v[2:5], v[164:167], v[132:135]
	ds_read_b64_tr_b16 v[156:157], v204 offset:45056
	ds_read_b64_tr_b16 v[158:159], v204 offset:47104
	v_exp_f32_e32 v56, v56
	v_mfma_f32_16x16x32_bf16 v[120:123], v[6:9], v[168:171], v[120:123]
	s_nop 0
	v_exp_f32_e32 v57, v57
	v_mfma_f32_16x16x32_bf16 v[124:127], v[2:5], v[168:171], v[124:127]
	ds_read_b64_tr_b16 v[160:161], v205 offset:45056
	ds_read_b64_tr_b16 v[162:163], v205 offset:47104
	v_exp_f32_e32 v46, v46
	s_waitcnt lgkmcnt(14)
	v_mfma_f32_16x16x32_bf16 v[106:109], v[6:9], v[148:151], v[106:109]
	s_nop 0
	v_exp_f32_e32 v47, v47
	v_mfma_f32_16x16x32_bf16 v[110:113], v[2:5], v[148:151], v[110:113]
	ds_read_b64_tr_b16 v[148:149], v206 offset:45056
	ds_read_b64_tr_b16 v[150:151], v206 offset:47104
	v_exp_f32_e32 v48, v48
	v_mfma_f32_16x16x32_bf16 v[98:101], v[6:9], v[172:175], v[98:101]
	s_nop 0
	v_exp_f32_e32 v49, v49
	v_mfma_f32_16x16x32_bf16 v[102:105], v[2:5], v[172:175], v[102:105]
	v_mfma_f32_16x16x32_bf16 v[18:21], v[34:37], v[26:29], v[18:21]
	v_exp_f32_e32 v38, v38
	v_cvt_pk_bf16_f32 v6, v116, v117
	s_waitcnt lgkmcnt(14)
	v_mfma_f32_16x16x32_bf16 v[58:61], v[34:37], v[140:143], v[22:25]
	v_mfma_f32_16x16x32_bf16 v[66:69], v[30:33], v[140:143], v[66:69]
	v_exp_f32_e32 v39, v39
	v_cvt_pk_bf16_f32 v7, v118, v119
	v_mfma_f32_16x16x32_bf16 v[22:25], v[30:33], v[26:29], v[62:65]
	s_waitcnt lgkmcnt(12)
	v_mfma_f32_16x16x32_bf16 v[62:65], v[34:37], v[70:73], v[74:77]
	v_exp_f32_e32 v40, v40
	v_cvt_pk_bf16_f32 v8, v54, v55
	v_mfma_f32_16x16x32_bf16 v[70:73], v[30:33], v[70:73], v[78:81]
	v_exp_f32_e32 v41, v41
	v_cvt_pk_bf16_f32 v9, v56, v57
	s_waitcnt lgkmcnt(10)
	v_mfma_f32_16x16x32_bf16 v[54:57], v[34:37], v[82:85], v[86:89]
	v_exp_f32_e32 v42, v42
	v_cvt_pk_bf16_f32 v2, v50, v51
	v_mfma_f32_16x16x32_bf16 v[74:77], v[30:33], v[82:85], v[90:93]
	v_exp_f32_e32 v43, v43
	v_cvt_pk_bf16_f32 v3, v52, v53
	s_waitcnt lgkmcnt(8)
	v_mfma_f32_16x16x32_bf16 v[50:53], v[34:37], v[136:139], v[144:147]
	v_exp_f32_e32 v44, v44
	v_cvt_pk_bf16_f32 v4, v46, v47
	v_mfma_f32_16x16x32_bf16 v[78:81], v[30:33], v[136:139], v[94:97]
	v_exp_f32_e32 v45, v45
	v_cvt_pk_bf16_f32 v5, v48, v49
	s_waitcnt lgkmcnt(6)
	v_mfma_f32_16x16x32_bf16 v[46:49], v[34:37], v[152:155], v[128:131]
	v_exp_f32_e32 v10, v10
	v_mfma_f32_16x16x32_bf16 v[82:85], v[30:33], v[152:155], v[132:135]
	v_exp_f32_e32 v11, v11
	s_nop 0
	v_exp_f32_e32 v12, v12
	s_waitcnt lgkmcnt(4)
	v_mfma_f32_16x16x32_bf16 v[86:89], v[34:37], v[156:159], v[120:123]
	s_nop 0
	v_exp_f32_e32 v13, v13
	v_mfma_f32_16x16x32_bf16 v[90:93], v[30:33], v[156:159], v[124:127]
	v_exp_f32_e32 v14, v14
	s_waitcnt lgkmcnt(2)
	v_mfma_f32_16x16x32_bf16 v[94:97], v[34:37], v[160:163], v[106:109]
	s_nop 0
	v_exp_f32_e32 v15, v15
	v_mfma_f32_16x16x32_bf16 v[106:109], v[30:33], v[160:163], v[110:113]
	s_waitcnt lgkmcnt(0)
	v_mfma_f32_16x16x32_bf16 v[34:37], v[34:37], v[148:151], v[98:101]
	v_exp_f32_e32 v16, v16
	v_mfma_f32_16x16x32_bf16 v[30:33], v[30:33], v[148:151], v[102:105]
	v_exp_f32_e32 v17, v17
	v_cvt_pk_bf16_f32 v98, v38, v39
	v_cvt_pk_bf16_f32 v99, v40, v41
	v_cvt_pk_bf16_f32 v100, v10, v11
	v_cvt_pk_bf16_f32 v101, v12, v13
	v_cvt_pk_bf16_f32 v102, v42, v43
	v_cvt_pk_bf16_f32 v103, v44, v45
	v_cvt_pk_bf16_f32 v104, v14, v15
	v_cvt_pk_bf16_f32 v105, v16, v17
	s_waitcnt vmcnt(0) lgkmcnt(0)
	s_barrier
; #define MF16(a, b, c) __builtin_amdgcn_mfma_f32_16x16x32_bf16(a, b, c, 0, 0, 0)
; #define MF16(a, b, c) __builtin_amdgcn_mfma_f32_16x16x32_bf16(a, b, c, 0, 0, 0)
; #define VRD16(f) do { vlo[f] = vtr(vpb[(f) & 3] + vo_ + (((f) >> 2) & 1) * 8192 + ((f) >> 3) * 4096); vhi[f] = vtr(vpb[(f) & 3] + vo_ + (((f) >> 2) & 1) * 8192 + ((f) >> 3) * 4096 + 2048); } while (0)
; __device__ __forceinline__ void attn_unit_d16(const UnitDesc& U, char* shm, float lam, const float* subw) {
;     ...
;     { constexpr int vo_ = 3 * VS;
; #pragma unroll
;       for (int f = 0; f < 16; ++f) { VRD16(f);
; #pragma unroll
;           for (int qt = 0; qt < 2; ++qt) o[qt][f & 7] = MF16(__builtin_bit_cast(bf16x8, pa[qt][f >> 3]), VFR16(f), o[qt][f & 7]); }
; #pragma unroll
;       for (int qt = 0; qt < 2; ++qt)
; #pragma unroll
;           for (int ks = 0; ks < 2; ++ks) ls[qt] = MF16(__builtin_bit_cast(bf16x8, pa[qt][ks]), onesb, ls[qt]); }
;     ...
;             for (int r = 0; r < 4; ++r) { const float sc = __builtin_amdgcn_rcpf(ls[qt][r]) * lam; const int row = 16 * qt + 4 * g_e + r;
;     ...
;             for (int r = 0; r < 4; ++r) { const float sc = __builtin_amdgcn_rcpf(ls[qt][r]); const int row = 16 * qt + 4 * g_e + r;
	ds_read_b64_tr_b16 v[10:11], v203 offset:49152
	ds_read_b64_tr_b16 v[12:13], v203 offset:51200
	ds_read_b64_tr_b16 v[14:15], v203 offset:53248
	ds_read_b64_tr_b16 v[16:17], v203 offset:55296
	v_mov_b32_e32 v1, v193
	s_lshl_b32 s10, s13, 14
	s_waitcnt lgkmcnt(2)
	v_mfma_f32_16x16x32_bf16 v[38:41], v[6:9], v[10:13], v[58:61]
	ds_read_b64_tr_b16 v[42:43], v204 offset:49152
	ds_read_b64_tr_b16 v[44:45], v204 offset:51200
	s_nop 0
	ds_read_b64_tr_b16 v[58:59], v204 offset:53248
	ds_read_b64_tr_b16 v[60:61], v204 offset:55296
	s_and_b32 s10, s10, 0xc000
	s_add_i32 s10, s10, 0
	v_mfma_f32_16x16x32_bf16 v[10:13], v[2:5], v[10:13], v[66:69]
	s_nop 2
	ds_read_b64_tr_b16 v[66:67], v205 offset:49152
	ds_read_b64_tr_b16 v[68:69], v205 offset:51200
	ds_read_b64_tr_b16 v[110:111], v205 offset:53248
	ds_read_b64_tr_b16 v[112:113], v205 offset:55296
	s_cmpk_gt_u32 s12, 0xff
	s_waitcnt lgkmcnt(6)
	v_mfma_f32_16x16x32_bf16 v[62:65], v[6:9], v[42:45], v[62:65]
	v_mfma_f32_16x16x32_bf16 v[42:45], v[2:5], v[42:45], v[70:73]
	s_nop 2
	ds_read_b64_tr_b16 v[70:71], v206 offset:49152
	ds_read_b64_tr_b16 v[72:73], v206 offset:51200
	ds_read_b64_tr_b16 v[116:117], v206 offset:53248
	ds_read_b64_tr_b16 v[118:119], v206 offset:55296
	s_waitcnt lgkmcnt(2)
	v_mfma_f32_16x16x32_bf16 v[50:53], v[6:9], v[70:73], v[50:53]
	v_mfma_f32_16x16x32_bf16 v[78:81], v[2:5], v[70:73], v[78:81]
	ds_read_b64_tr_b16 v[70:71], v203 offset:57344
	ds_read_b64_tr_b16 v[72:73], v203 offset:59392
	ds_read_b64_tr_b16 v[120:121], v203 offset:61440
	ds_read_b64_tr_b16 v[122:123], v203 offset:63488
	s_waitcnt lgkmcnt(2)
	v_mfma_f32_16x16x32_bf16 v[46:49], v[6:9], v[70:73], v[46:49]
	v_mfma_f32_16x16x32_bf16 v[82:85], v[2:5], v[70:73], v[82:85]
	ds_read_b64_tr_b16 v[70:71], v204 offset:57344
	ds_read_b64_tr_b16 v[72:73], v204 offset:59392
	ds_read_b64_tr_b16 v[124:125], v204 offset:61440
	ds_read_b64_tr_b16 v[126:127], v204 offset:63488
	s_waitcnt lgkmcnt(2)
	v_mfma_f32_16x16x32_bf16 v[86:89], v[6:9], v[70:73], v[86:89]
	v_mfma_f32_16x16x32_bf16 v[90:93], v[2:5], v[70:73], v[90:93]
	ds_read_b64_tr_b16 v[70:71], v205 offset:57344
	ds_read_b64_tr_b16 v[72:73], v205 offset:59392
	ds_read_b64_tr_b16 v[128:129], v205 offset:61440
	ds_read_b64_tr_b16 v[130:131], v205 offset:63488
	s_waitcnt lgkmcnt(2)
	v_mfma_f32_16x16x32_bf16 v[94:97], v[6:9], v[70:73], v[94:97]
	v_mfma_f32_16x16x32_bf16 v[106:109], v[2:5], v[70:73], v[106:109]
	ds_read_b64_tr_b16 v[70:71], v206 offset:57344
	ds_read_b64_tr_b16 v[72:73], v206 offset:59392
	ds_read_b64_tr_b16 v[132:133], v206 offset:61440
	ds_read_b64_tr_b16 v[134:135], v206 offset:63488
	s_waitcnt lgkmcnt(0)
	s_barrier
	v_mfma_f32_16x16x32_bf16 v[54:57], v[6:9], v[66:69], v[54:57]
	v_mfma_f32_16x16x32_bf16 v[66:69], v[2:5], v[66:69], v[74:77]
	s_waitcnt lgkmcnt(2)
	v_mfma_f32_16x16x32_bf16 v[136:139], v[6:9], v[70:73], v[34:37]
	v_mfma_f32_16x16x32_bf16 v[140:143], v[2:5], v[70:73], v[30:33]
	v_mfma_f32_16x16x32_bf16 v[6:9], v[6:9], v[26:29], v[18:21]
	v_mfma_f32_16x16x32_bf16 v[2:5], v[2:5], v[26:29], v[22:25]
	v_mfma_f32_16x16x32_bf16 v[74:77], v[98:101], v[58:61], v[62:65]
	v_mfma_f32_16x16x32_bf16 v[42:45], v[102:105], v[58:61], v[42:45]
	v_mfma_f32_16x16x32_bf16 v[58:61], v[98:101], v[110:113], v[54:57]
	v_mfma_f32_16x16x32_bf16 v[54:57], v[98:101], v[124:127], v[86:89]
	v_mfma_f32_16x16x32_bf16 v[86:89], v[98:101], v[26:29], v[6:9]
	v_mfma_f32_16x16x32_bf16 v[2:5], v[102:105], v[26:29], v[2:5]
	v_mfma_f32_16x16x32_bf16 v[70:73], v[98:101], v[14:17], v[38:41]
	s_nop 5
	v_rcp_f32_e32 v21, v86
	v_rcp_f32_e32 v20, v87
	v_rcp_f32_e32 v19, v88
	v_mfma_f32_16x16x32_bf16 v[38:41], v[102:105], v[14:17], v[10:13]
	v_rcp_f32_e32 v18, v89
	v_rcp_f32_e32 v9, v2
	v_rcp_f32_e32 v8, v3
	v_mfma_f32_16x16x32_bf16 v[10:13], v[102:105], v[120:123], v[82:85]
	s_nop 2
	v_and_b32_e32 v84, 15, v1
	v_ashrrev_i32_e32 v82, 4, v1
	v_lshlrev_b32_e32 v1, 11, v82
	v_lshlrev_b32_e32 v6, 2, v84
	v_mfma_f32_16x16x32_bf16 v[30:33], v[102:105], v[110:113], v[66:69]
	v_add3_u32 v7, s10, v6, v1
	v_rcp_f32_e32 v6, v4
	v_rcp_f32_e32 v1, v5
	v_mfma_f32_16x16x32_bf16 v[62:65], v[98:101], v[116:119], v[50:53]
	v_mfma_f32_16x16x32_bf16 v[34:37], v[102:105], v[116:119], v[78:81]
	v_mfma_f32_16x16x32_bf16 v[66:69], v[98:101], v[120:123], v[46:49]
	v_mfma_f32_16x16x32_bf16 v[14:17], v[102:105], v[124:127], v[90:93]
	v_mfma_f32_16x16x32_bf16 v[50:53], v[98:101], v[128:131], v[94:97]
	v_mfma_f32_16x16x32_bf16 v[46:49], v[102:105], v[128:131], v[106:109]
	s_waitcnt lgkmcnt(0)
	v_mfma_f32_16x16x32_bf16 v[78:81], v[98:101], v[132:135], v[136:139]
	v_mfma_f32_16x16x32_bf16 v[2:5], v[102:105], v[132:135], v[140:143]
	s_cbranch_scc0 .LBB0_447
; __device__ __forceinline__ void attn_unit_d16(const UnitDesc& U, char* shm, float lam, const float* subw) {
;     ...
;     if (wid >= 4) {
; #pragma unroll
;         for (int qt = 0; qt < 2; ++qt)
; #pragma unroll
;             for (int r = 0; r < 4; ++r) { const float sc = __builtin_amdgcn_rcpf(ls[qt][r]) * lam; const int row = 16 * qt + 4 * g_e + r;
; #pragma unroll
;                 for (int dt = 0; dt < 8; ++dt) X[row * 128 + 16 * dt + c16_e] = o[qt][dt][r] * sc; }
;     }
	v_mul_f32_e32 v22, v181, v21
	v_mul_f32_e32 v23, v70, v22
	v_mul_f32_e32 v24, v74, v22
	ds_write2_b32 v7, v23, v24 offset1:16
	v_mul_f32_e32 v23, v58, v22
	v_mul_f32_e32 v24, v62, v22
	ds_write2_b32 v7, v23, v24 offset0:32 offset1:48
	v_mul_f32_e32 v23, v66, v22
	v_mul_f32_e32 v24, v54, v22
	ds_write2_b32 v7, v23, v24 offset0:64 offset1:80
	v_mul_f32_e32 v23, v50, v22
	v_mul_f32_e32 v22, v78, v22
	ds_write2_b32 v7, v23, v22 offset0:96 offset1:112
	v_mul_f32_e32 v22, v181, v20
	v_mul_f32_e32 v23, v71, v22
	v_mul_f32_e32 v24, v75, v22
	ds_write2_b32 v7, v23, v24 offset0:128 offset1:144
	v_mul_f32_e32 v23, v59, v22
	v_mul_f32_e32 v24, v63, v22
	ds_write2_b32 v7, v23, v24 offset0:160 offset1:176
	v_mul_f32_e32 v23, v67, v22
	v_mul_f32_e32 v24, v55, v22
	ds_write2_b32 v7, v23, v24 offset0:192 offset1:208
	v_mul_f32_e32 v23, v51, v22
	v_mul_f32_e32 v22, v79, v22
	ds_write2_b32 v7, v23, v22 offset0:224 offset1:240
	v_mul_f32_e32 v22, v181, v19
	v_mul_f32_e32 v23, v72, v22
	v_mul_f32_e32 v24, v76, v22
	v_add_u32_e32 v25, 0x400, v7
	ds_write2_b32 v25, v23, v24 offset1:16
	v_mul_f32_e32 v23, v60, v22
	v_mul_f32_e32 v24, v64, v22
	ds_write2_b32 v25, v23, v24 offset0:32 offset1:48
	v_mul_f32_e32 v23, v68, v22
	v_mul_f32_e32 v24, v56, v22
	ds_write2_b32 v25, v23, v24 offset0:64 offset1:80
	v_mul_f32_e32 v23, v52, v22
	v_mul_f32_e32 v22, v80, v22
	ds_write2_b32 v25, v23, v22 offset0:96 offset1:112
	v_mul_f32_e32 v22, v181, v18
	v_mul_f32_e32 v23, v73, v22
	v_mul_f32_e32 v24, v77, v22
	ds_write2_b32 v25, v23, v24 offset0:128 offset1:144
	v_mul_f32_e32 v23, v61, v22
	v_mul_f32_e32 v24, v65, v22
	ds_write2_b32 v25, v23, v24 offset0:160 offset1:176
	v_mul_f32_e32 v23, v69, v22
	v_mul_f32_e32 v24, v57, v22
	ds_write2_b32 v25, v23, v24 offset0:192 offset1:208
	v_mul_f32_e32 v23, v53, v22
	v_mul_f32_e32 v22, v81, v22
	ds_write2_b32 v25, v23, v22 offset0:224 offset1:240
	v_mul_f32_e32 v22, v181, v9
	v_mul_f32_e32 v23, v38, v22
	v_mul_f32_e32 v24, v42, v22
	v_add_u32_e32 v25, 0x2000, v7
	ds_write2_b32 v25, v23, v24 offset1:16
	v_mul_f32_e32 v23, v30, v22
	v_mul_f32_e32 v24, v34, v22
	ds_write2_b32 v25, v23, v24 offset0:32 offset1:48
	v_mul_f32_e32 v23, v10, v22
	v_mul_f32_e32 v24, v14, v22
	ds_write2_b32 v25, v23, v24 offset0:64 offset1:80
	v_mul_f32_e32 v23, v46, v22
	v_mul_f32_e32 v22, v2, v22
	ds_write2_b32 v25, v23, v22 offset0:96 offset1:112
	v_mul_f32_e32 v22, v181, v8
	v_mul_f32_e32 v23, v39, v22
	v_mul_f32_e32 v24, v43, v22
	ds_write2_b32 v25, v23, v24 offset0:128 offset1:144
	v_mul_f32_e32 v23, v31, v22
	v_mul_f32_e32 v24, v35, v22
	ds_write2_b32 v25, v23, v24 offset0:160 offset1:176
	v_mul_f32_e32 v23, v11, v22
	v_mul_f32_e32 v24, v15, v22
	ds_write2_b32 v25, v23, v24 offset0:192 offset1:208
	v_mul_f32_e32 v23, v47, v22
	v_mul_f32_e32 v22, v3, v22
	ds_write2_b32 v25, v23, v22 offset0:224 offset1:240
	v_mul_f32_e32 v22, v181, v6
	v_mul_f32_e32 v23, v40, v22
	v_mul_f32_e32 v24, v44, v22
	v_add_u32_e32 v25, 0x2400, v7
	ds_write2_b32 v25, v23, v24 offset1:16
	v_mul_f32_e32 v23, v32, v22
	v_mul_f32_e32 v24, v36, v22
	ds_write2_b32 v25, v23, v24 offset0:32 offset1:48
	v_mul_f32_e32 v23, v12, v22
	v_mul_f32_e32 v24, v16, v22
	ds_write2_b32 v25, v23, v24 offset0:64 offset1:80
	v_mul_f32_e32 v23, v48, v22
	v_mul_f32_e32 v22, v4, v22
	ds_write2_b32 v25, v23, v22 offset0:96 offset1:112
	v_mul_f32_e32 v22, v181, v1
	v_mul_f32_e32 v23, v41, v22
	v_mul_f32_e32 v24, v45, v22
	ds_write2_b32 v25, v23, v24 offset0:128 offset1:144
	v_mul_f32_e32 v23, v33, v22
	v_mul_f32_e32 v24, v37, v22
	ds_write2_b32 v25, v23, v24 offset0:160 offset1:176
	v_mul_f32_e32 v23, v13, v22
	v_mul_f32_e32 v24, v17, v22
	ds_write2_b32 v25, v23, v24 offset0:192 offset1:208
	v_mul_f32_e32 v23, v49, v22
	v_mul_f32_e32 v22, v5, v22
	ds_write2_b32 v25, v23, v22 offset0:224 offset1:240
